# speedup vs baseline: 1.0164x; 1.0055x over previous
; __device__ __forceinline__ void finishSM(f32x16& p0, f32x16& p1, float alpha, float& l_reg, bf16x8& pa0, bf16x8& pa1, bf16x8& pa2, bf16x8& pa3) {
; #pragma unroll
;   for (int r = 0; r < 16; ++r) p1[r] = __builtin_amdgcn_exp2f(p1[r]);
;   float ps = 0;
; #pragma unroll
;   for (int r = 0; r < 16; ++r) ps += p0[r];
; #pragma unroll
;   for (int r = 0; r < 16; ++r) ps += p1[r];
;   { auto rr = __builtin_amdgcn_permlane32_swap(__float_as_uint(ps), __float_as_uint(ps), false, false);
;     ps = __uint_as_float(rr[0]) + __uint_as_float(rr[1]); }
;   l_reg = l_reg * alpha + ps;
;     ...
;   PK4(p0, 0, pa0); PK4(p0, 8, pa1); PK4(p1, 0, pa2); PK4(p1, 8, pa3);
;     ...
; }
; template <int DQK>
; __device__ __forceinline__ void qkt(f32x16& p0, f32x16& p1, const bf16* Ks, const bf16x8* qr, int r32, int hi, int k0, int L) {
;   p0 = f32x16{}; p1 = f32x16{};
; #pragma unroll
;   for (int d0 = 0; d0 < DQK / 16; ++d0) { int cb = (d0 * 16 + hi * 8) * 2;
;     bf16x8 b0 = *reinterpret_cast<const bf16x8*>((const char*)Ks + KSWZ(r32, cb));
;     bf16x8 b1 = *reinterpret_cast<const bf16x8*>((const char*)Ks + KSWZ(32 + r32, cb));
;     p0 = __builtin_amdgcn_mfma_f32_32x32x16_bf16(b0, qr[d0], p0, 0, 0, 0);
;     p1 = __builtin_amdgcn_mfma_f32_32x32x16_bf16(b1, qr[d0], p1, 0, 0, 0); }
;   if (k0 + KVBLK > L) {
; #pragma unroll
;     for (int r = 0; r < 16; ++r) { const int key = k0 + crow(r, hi);
;       if (key >= L) p0[r] = -1e30f;
;       if (key + 32 >= L) p1[r] = -1e30f; }
;   }
; }
; __device__ __forceinline__ int v_st(int k, int c) { const int kk = (k & ~0xC) | ((k & 4) << 1) | ((k & 8) >> 1); return ((kk >> 3) * 4 + (c >> 5)) * 512 + ((kk & 7) * 32 + (c & 31)) * 2; }
; __device__ __forceinline__ int v_rd_base(int lane) { return ((lane & 3) << 3) | (((lane >> 2) & 3) << 6) | (((lane >> 4) & 1) << 5) | (((lane >> 5) & 1) << 8); }
; template <int OFF> __device__ __forceinline__ s16x4 tr_read(int vb) {
;   s16x4 r; asm volatile("ds_read_b64_tr_b16 %0, %1 offset:%2" : "=&v"(r) : "v"(vb), "i"(OFF) : "memory"); return r;
; }
; template <int D0> __device__ __forceinline__ void pv_one(f32x16& od, int vb, bf16x8 pa0, bf16x8 pa1, bf16x8 pa2, bf16x8 pa3) {
;   const s16x4 l0 = tr_read<v_rd_off(D0, 0, 0)>(vb), h0 = tr_read<v_rd_off(D0, 0, 1)>(vb), l1 = tr_read<v_rd_off(D0, 1, 0)>(vb), h1 = tr_read<v_rd_off(D0, 1, 1)>(vb);
.LBB0_832:
	s_and_saveexec_b64 s[2:3], s[8:9]
	s_cbranch_execz .LBB0_838
	s_add_i32 s6, s78, 64
	s_cmp_le_u32 s6, s79
	s_cbranch_scc0 .Lslow64a
	s_and_b64 vcc, exec, s[10:11]
	s_cbranch_vccz .Lslow64a
	ds_read_b128 v[222:225], v167 offset:49152
	ds_read_b128 v[226:229], v168 offset:49152
	ds_read_b128 v[230:233], v167 offset:57344
	ds_read_b128 v[234:237], v168 offset:57344
	ds_read_b128 v[238:241], v169 offset:49152
	ds_read_b128 v[242:245], v169 offset:57344
	ds_read_b128 v[246:249], v171 offset:49152
	ds_read_b128 v[250:253], v171 offset:57344
	v_cvt_pk_bf16_f32 v130, v50, v51
	v_cvt_pk_bf16_f32 v131, v52, v53
	v_cvt_pk_bf16_f32 v132, v54, v55
	v_cvt_pk_bf16_f32 v133, v56, v57
	v_cvt_pk_bf16_f32 v134, v58, v59
	v_cvt_pk_bf16_f32 v135, v60, v61
	v_cvt_pk_bf16_f32 v136, v62, v63
	v_cvt_pk_bf16_f32 v137, v64, v65
	s_waitcnt lgkmcnt(7)
	v_mfma_f32_32x32x16_bf16 v[66:81], v[222:225], v[98:101], 0
	ds_read_b64_tr_b16 v[186:187], v166 offset:0
	ds_read_b64_tr_b16 v[188:189], v166 offset:2048
	ds_read_b64_tr_b16 v[190:191], v166 offset:4096
	ds_read_b64_tr_b16 v[192:193], v166 offset:6144
	v_permlane32_swap_b32_e32 v130, v132
	v_permlane32_swap_b32_e32 v131, v133
	v_permlane32_swap_b32_e32 v134, v136
	v_permlane32_swap_b32_e32 v135, v137
	s_waitcnt lgkmcnt(10)
	v_mfma_f32_32x32x16_bf16 v[66:81], v[226:229], v[102:105], v[66:81]
	ds_read_b64_tr_b16 v[194:195], v166 offset:8192
	ds_read_b64_tr_b16 v[196:197], v166 offset:10240
	ds_read_b64_tr_b16 v[198:199], v166 offset:12288
	ds_read_b64_tr_b16 v[200:201], v166 offset:14336
	v_exp_f32_e32 v34, v34
	v_exp_f32_e32 v35, v35
	v_exp_f32_e32 v36, v36
	s_waitcnt lgkmcnt(13)
	v_mfma_f32_32x32x16_bf16 v[82:97], v[230:233], v[98:101], 0
	v_exp_f32_e32 v37, v37
	v_exp_f32_e32 v38, v38
	v_exp_f32_e32 v39, v39
	s_waitcnt lgkmcnt(12)
	v_mfma_f32_32x32x16_bf16 v[82:97], v[234:237], v[102:105], v[82:97]
	v_exp_f32_e32 v40, v40
	v_exp_f32_e32 v41, v41
	v_exp_f32_e32 v42, v42
	s_waitcnt lgkmcnt(11)
	v_mfma_f32_32x32x16_bf16 v[66:81], v[238:241], v[106:109], v[66:81]
	v_exp_f32_e32 v43, v43
	v_exp_f32_e32 v44, v44
	v_exp_f32_e32 v45, v45
	s_waitcnt lgkmcnt(10)
	v_mfma_f32_32x32x16_bf16 v[82:97], v[242:245], v[106:109], v[82:97]
	ds_read_b64_tr_b16 v[222:223], v166 offset:512
	ds_read_b64_tr_b16 v[224:225], v166 offset:2560
	ds_read_b64_tr_b16 v[226:227], v166 offset:4608
	ds_read_b64_tr_b16 v[228:229], v166 offset:6656
	v_exp_f32_e32 v46, v46
	v_exp_f32_e32 v47, v47
	v_exp_f32_e32 v48, v48
	s_waitcnt lgkmcnt(13)
	v_mfma_f32_32x32x16_bf16 v[66:81], v[246:249], v[110:113], v[66:81]
	v_exp_f32_e32 v49, v49
	v_cvt_pk_bf16_f32 v138, v34, v35
	v_cvt_pk_bf16_f32 v139, v36, v37
	v_cvt_pk_bf16_f32 v140, v38, v39
	v_cvt_pk_bf16_f32 v141, v40, v41
	s_waitcnt lgkmcnt(12)
	v_mfma_f32_32x32x16_bf16 v[82:97], v[250:253], v[110:113], v[82:97]
	ds_read_b64_tr_b16 v[230:231], v166 offset:8704
	ds_read_b64_tr_b16 v[232:233], v166 offset:10752
	ds_read_b64_tr_b16 v[234:235], v166 offset:12800
	s_waitcnt lgkmcnt(14)
	ds_read_b64_tr_b16 v[236:237], v166 offset:14848
	v_cvt_pk_bf16_f32 v142, v42, v43
	v_cvt_pk_bf16_f32 v143, v44, v45
	v_cvt_pk_bf16_f32 v144, v46, v47
	v_cvt_pk_bf16_f32 v145, v48, v49
	s_nop 0
	v_permlane32_swap_b32_e32 v138, v140
	v_permlane32_swap_b32_e32 v139, v141
	v_permlane32_swap_b32_e32 v142, v144
	v_permlane32_swap_b32_e32 v143, v145
	s_or_b64 exec, exec, s[2:3]
	v_lshl_add_u64 v[152:153], v[148:149], 0, s[4:5]
	v_add_co_u32_e32 v122, vcc, 0x2ced0000, v152
	v_lshl_add_u64 v[150:151], v[146:147], 0, s[4:5]
	s_nop 0
	v_addc_co_u32_e32 v123, vcc, 0, v153, vcc
	v_add_co_u32_e32 v126, vcc, 0x119cc000, v150
	global_load_dwordx4 v[122:125], v[122:123], off offset:2048
	s_nop 0
	v_addc_co_u32_e32 v127, vcc, 0, v151, vcc
	global_load_dwordx4 v[126:129], v[126:127], off
	s_and_saveexec_b64 s[2:3], s[8:9]
	s_waitcnt lgkmcnt(14)
	v_mfma_f32_32x32x16_bf16 v[2:17], v[130:133], v[186:189], v[2:17]
	v_add_f32_e32 v252, 0, v50
	v_add_f32_e32 v252, v51, v252
	v_add_f32_e32 v252, v52, v252
	v_add_f32_e32 v252, v53, v252
	v_exp_f32_e32 v66, v66
	v_exp_f32_e32 v67, v67
	s_waitcnt lgkmcnt(12)
	v_mfma_f32_32x32x16_bf16 v[2:17], v[134:137], v[190:193], v[2:17]
	v_add_f32_e32 v252, v54, v252
	v_add_f32_e32 v252, v55, v252
	v_add_f32_e32 v252, v56, v252
	v_add_f32_e32 v252, v57, v252
	v_exp_f32_e32 v68, v68
	v_exp_f32_e32 v69, v69
	s_waitcnt lgkmcnt(10)
	v_mfma_f32_32x32x16_bf16 v[2:17], v[138:141], v[194:197], v[2:17]
	v_add_f32_e32 v252, v58, v252
	v_add_f32_e32 v252, v59, v252
	v_add_f32_e32 v252, v60, v252
	v_add_f32_e32 v252, v61, v252
	v_exp_f32_e32 v70, v70
	v_exp_f32_e32 v71, v71
	s_waitcnt lgkmcnt(8)
	v_mfma_f32_32x32x16_bf16 v[2:17], v[142:145], v[198:201], v[2:17]
	v_add_f32_e32 v252, v62, v252
	v_add_f32_e32 v252, v63, v252
	v_add_f32_e32 v252, v64, v252
	v_add_f32_e32 v252, v65, v252
	v_exp_f32_e32 v72, v72
	v_exp_f32_e32 v73, v73
	s_waitcnt lgkmcnt(6)
	v_mfma_f32_32x32x16_bf16 v[18:33], v[130:133], v[222:225], v[18:33]
	v_add_f32_e32 v252, v34, v252
	v_add_f32_e32 v252, v35, v252
	v_add_f32_e32 v252, v36, v252
	v_add_f32_e32 v252, v37, v252
	v_exp_f32_e32 v74, v74
	v_exp_f32_e32 v75, v75
	s_waitcnt lgkmcnt(4)
	v_mfma_f32_32x32x16_bf16 v[18:33], v[134:137], v[226:229], v[18:33]
	v_add_f32_e32 v252, v38, v252
	v_add_f32_e32 v252, v39, v252
	v_add_f32_e32 v252, v40, v252
	v_add_f32_e32 v252, v41, v252
	v_exp_f32_e32 v76, v76
	v_exp_f32_e32 v77, v77
	s_waitcnt lgkmcnt(2)
	v_mfma_f32_32x32x16_bf16 v[18:33], v[138:141], v[230:233], v[18:33]
	v_add_f32_e32 v252, v42, v252
	v_add_f32_e32 v252, v43, v252
	v_add_f32_e32 v252, v44, v252
	v_add_f32_e32 v252, v45, v252
	v_exp_f32_e32 v78, v78
	v_exp_f32_e32 v79, v79
	s_waitcnt lgkmcnt(0)
	v_mfma_f32_32x32x16_bf16 v[18:33], v[142:145], v[234:237], v[18:33]
	v_add_f32_e32 v252, v46, v252
	v_add_f32_e32 v252, v47, v252
	v_add_f32_e32 v252, v48, v252
	v_add_f32_e32 v252, v49, v252
	v_exp_f32_e32 v80, v80
	v_exp_f32_e32 v81, v81
	v_mov_b32_e32 v253, v252
	s_nop 1
	v_permlane32_swap_b32_e32 v252, v253
	v_add_f32_e32 v252, v252, v253
	v_add_f32_e32 v163, v163, v252
	s_branch .LBB0_842
; __device__ __forceinline__ int crow(int r, int hi) { return (r & 3) + 8 * (r >> 2) + 4 * hi; }
; template <int DQK>
; __device__ __forceinline__ void qkt(f32x16& p0, f32x16& p1, const bf16* Ks, const bf16x8* qr, int r32, int hi, int k0, int L) {
;   p0 = f32x16{}; p1 = f32x16{};
; #pragma unroll
;   for (int d0 = 0; d0 < DQK / 16; ++d0) { int cb = (d0 * 16 + hi * 8) * 2;
;     bf16x8 b0 = *reinterpret_cast<const bf16x8*>((const char*)Ks + KSWZ(r32, cb));
;     bf16x8 b1 = *reinterpret_cast<const bf16x8*>((const char*)Ks + KSWZ(32 + r32, cb));
;     p0 = __builtin_amdgcn_mfma_f32_32x32x16_bf16(b0, qr[d0], p0, 0, 0, 0);
;     p1 = __builtin_amdgcn_mfma_f32_32x32x16_bf16(b1, qr[d0], p1, 0, 0, 0); }
;   if (k0 + KVBLK > L) {
; #pragma unroll
;     for (int r = 0; r < 16; ++r) { const int key = k0 + crow(r, hi);
;       if (key >= L) p0[r] = -1e30f;
;       if (key + 32 >= L) p1[r] = -1e30f; }
;   }
.Lslow64a:
	ds_read_b128 v[222:225], v167 offset:49152
	ds_read_b128 v[226:229], v168 offset:49152
	ds_read_b128 v[230:233], v167 offset:57344
	ds_read_b128 v[234:237], v168 offset:57344
	ds_read_b128 v[238:241], v169 offset:49152
	ds_read_b128 v[242:245], v169 offset:57344
	ds_read_b128 v[246:249], v171 offset:49152
	ds_read_b128 v[250:253], v171 offset:57344
	s_add_i32 s6, s78, 64
	s_cmp_le_u32 s6, s79
	s_waitcnt lgkmcnt(7)
	v_mfma_f32_32x32x16_bf16 v[66:81], v[222:225], v[98:101], 0
	s_waitcnt lgkmcnt(6)
	v_mfma_f32_32x32x16_bf16 v[66:81], v[226:229], v[102:105], v[66:81]
	s_waitcnt lgkmcnt(5)
	v_mfma_f32_32x32x16_bf16 v[82:97], v[230:233], v[98:101], 0
	s_waitcnt lgkmcnt(4)
	v_mfma_f32_32x32x16_bf16 v[82:97], v[234:237], v[102:105], v[82:97]
	s_waitcnt lgkmcnt(3)
	v_mfma_f32_32x32x16_bf16 v[66:81], v[238:241], v[106:109], v[66:81]
	s_waitcnt lgkmcnt(2)
	v_mfma_f32_32x32x16_bf16 v[82:97], v[242:245], v[106:109], v[82:97]
	s_waitcnt lgkmcnt(1)
	v_mfma_f32_32x32x16_bf16 v[66:81], v[246:249], v[110:113], v[66:81]
	s_waitcnt lgkmcnt(0)
	v_mfma_f32_32x32x16_bf16 v[82:97], v[250:253], v[110:113], v[82:97]
	s_cbranch_scc1 .LBB0_837
	v_add_u32_e32 v122, s78, v162
	v_add_u32_e32 v123, 64, v122
	v_cmp_gt_u32_e32 vcc, s96, v123
	v_cmp_gt_u32_e64 s[42:43], s72, v123
	v_add_u32_e32 v123, 0x41, v122
	v_cmp_gt_u32_e64 s[12:13], s96, v123
	v_cmp_gt_u32_e64 s[44:45], s72, v123
	v_add_u32_e32 v123, 0x42, v122
	v_cmp_gt_u32_e64 s[14:15], s96, v123
	v_cmp_gt_u32_e64 s[46:47], s72, v123
	v_add_u32_e32 v123, 0x43, v122
	v_cmp_gt_u32_e64 s[16:17], s96, v123
	v_cmp_gt_u32_e64 s[48:49], s72, v123
	v_add_u32_e32 v123, 0x48, v122
	v_cmp_gt_u32_e64 s[18:19], s96, v123
	v_cmp_gt_u32_e64 s[50:51], s72, v123
	v_add_u32_e32 v123, 0x49, v122
	v_cmp_gt_u32_e64 s[20:21], s96, v123
	v_cmp_gt_u32_e64 s[52:53], s72, v123
	v_add_u32_e32 v123, 0x4a, v122
	v_cmp_gt_u32_e64 s[22:23], s96, v123
	v_cmp_gt_u32_e64 s[54:55], s72, v123
	v_add_u32_e32 v123, 0x4b, v122
	v_cmp_gt_u32_e64 s[24:25], s96, v123
	v_cmp_gt_u32_e64 s[56:57], s72, v123
	v_add_u32_e32 v123, 0x50, v122
	v_cmp_gt_u32_e64 s[26:27], s96, v123
	v_cmp_gt_u32_e64 s[58:59], s72, v123
	v_add_u32_e32 v123, 0x51, v122
	v_cmp_gt_u32_e64 s[28:29], s96, v123
	v_cmp_gt_u32_e64 s[60:61], s72, v123
	v_add_u32_e32 v123, 0x52, v122
	v_cmp_gt_u32_e64 s[30:31], s96, v123
	v_cmp_gt_u32_e64 s[62:63], s72, v123
	v_add_u32_e32 v123, 0x53, v122
	v_cmp_gt_u32_e64 s[34:35], s96, v123
	v_cmp_gt_u32_e64 s[64:65], s72, v123
	v_add_u32_e32 v123, 0x58, v122
	v_cmp_gt_u32_e64 s[36:37], s96, v123
	v_cmp_gt_u32_e64 s[66:67], s72, v123
	v_add_u32_e32 v123, 0x59, v122
	v_cmp_gt_u32_e64 s[38:39], s96, v123
	v_cmp_gt_u32_e64 s[68:69], s72, v123
	v_add_u32_e32 v123, 0x5a, v122
	v_cmp_gt_u32_e64 s[70:71], s72, v123
	s_or_b64 s[68:69], s[70:71], s[68:69]
	s_or_b64 s[66:67], s[68:69], s[66:67]
	s_or_b64 s[64:65], s[66:67], s[64:65]
	s_or_b64 s[62:63], s[64:65], s[62:63]
	s_or_b64 s[60:61], s[62:63], s[60:61]
	s_or_b64 s[58:59], s[60:61], s[58:59]
	s_or_b64 s[56:57], s[58:59], s[56:57]
	s_or_b64 s[54:55], s[56:57], s[54:55]
	s_or_b64 s[52:53], s[54:55], s[52:53]
	s_or_b64 s[50:51], s[52:53], s[50:51]
	s_or_b64 s[48:49], s[50:51], s[48:49]
	s_or_b64 s[46:47], s[48:49], s[46:47]
	s_or_b64 s[44:45], s[46:47], s[44:45]
	s_or_b64 s[42:43], s[44:45], s[42:43]
	v_add_u32_e32 v122, 0x5b, v122
	v_cmp_gt_u32_e64 s[40:41], s96, v123
	v_cndmask_b32_e64 v96, v184, v96, s[70:71]
	v_cndmask_b32_e64 v95, v184, v95, s[68:69]
	v_cndmask_b32_e64 v94, v184, v94, s[66:67]
	v_cndmask_b32_e64 v93, v184, v93, s[64:65]
	v_cndmask_b32_e64 v92, v184, v92, s[62:63]
	v_cndmask_b32_e64 v91, v184, v91, s[60:61]
	v_cndmask_b32_e64 v90, v184, v90, s[58:59]
	v_cndmask_b32_e64 v89, v184, v89, s[56:57]
	v_cndmask_b32_e64 v88, v184, v88, s[54:55]
	v_cndmask_b32_e64 v87, v184, v87, s[52:53]
	v_cndmask_b32_e64 v86, v184, v86, s[50:51]
	v_cndmask_b32_e64 v85, v184, v85, s[48:49]
	v_cndmask_b32_e64 v84, v184, v84, s[46:47]
	v_cndmask_b32_e64 v83, v184, v83, s[44:45]
	v_cndmask_b32_e64 v82, v184, v82, s[42:43]
	v_cmp_gt_u32_e64 s[42:43], s96, v122
	v_cmp_le_u32_e64 s[44:45], s72, v122
	s_and_saveexec_b64 s[6:7], s[44:45]
	s_mov_b32 s44, 0xf149f2ca
	v_mov_b32_e32 v97, s44
	s_or_b64 exec, exec, s[6:7]
	s_or_b64 s[40:41], s[42:43], s[40:41]
	s_or_b64 s[38:39], s[40:41], s[38:39]
	s_or_b64 s[36:37], s[38:39], s[36:37]
	s_or_b64 s[34:35], s[36:37], s[34:35]
	s_or_b64 s[30:31], s[34:35], s[30:31]
	s_or_b64 s[28:29], s[30:31], s[28:29]
	s_or_b64 s[26:27], s[28:29], s[26:27]
	s_or_b64 s[24:25], s[26:27], s[24:25]
	s_or_b64 s[22:23], s[24:25], s[22:23]
	s_or_b64 s[20:21], s[22:23], s[20:21]
	s_or_b64 s[18:19], s[20:21], s[18:19]
	s_or_b64 s[16:17], s[18:19], s[16:17]
	s_or_b64 s[14:15], s[16:17], s[14:15]
	s_or_b64 s[12:13], s[14:15], s[12:13]
	s_or_b64 vcc, s[12:13], vcc
	v_cndmask_b32_e64 v80, v184, v80, s[40:41]
	v_cndmask_b32_e64 v79, v184, v79, s[38:39]
	v_cndmask_b32_e64 v78, v184, v78, s[36:37]
	v_cndmask_b32_e64 v77, v184, v77, s[34:35]
	v_cndmask_b32_e64 v76, v184, v76, s[30:31]
	v_cndmask_b32_e64 v75, v184, v75, s[28:29]
	v_cndmask_b32_e64 v74, v184, v74, s[26:27]
	v_cndmask_b32_e64 v73, v184, v73, s[24:25]
	v_cndmask_b32_e64 v72, v184, v72, s[22:23]
	v_cndmask_b32_e64 v71, v184, v71, s[20:21]
	v_cndmask_b32_e64 v70, v184, v70, s[18:19]
	v_cndmask_b32_e64 v69, v184, v69, s[16:17]
	v_cndmask_b32_e64 v68, v184, v68, s[14:15]
	v_cndmask_b32_e64 v67, v184, v67, s[12:13]
	v_cndmask_b32_e32 v66, v184, v66, vcc
	v_cndmask_b32_e64 v81, v184, v81, s[42:43]
	s_movk_i32 s65, 0x600
	s_mov_b64 s[66:67], 0x80
	s_mov_b64 s[68:69], 0x1e90c900

; __device__ __forceinline__ void finishSM(f32x16& p0, f32x16& p1, float alpha, float& l_reg, bf16x8& pa0, bf16x8& pa1, bf16x8& pa2, bf16x8& pa3) {
; #pragma unroll
;   for (int r = 0; r < 16; ++r) p1[r] = __builtin_amdgcn_exp2f(p1[r]);
;   float ps = 0;
; #pragma unroll
;   for (int r = 0; r < 16; ++r) ps += p0[r];
; #pragma unroll
;   for (int r = 0; r < 16; ++r) ps += p1[r];
;   { auto rr = __builtin_amdgcn_permlane32_swap(__float_as_uint(ps), __float_as_uint(ps), false, false);
;     ps = __uint_as_float(rr[0]) + __uint_as_float(rr[1]); }
;   l_reg = l_reg * alpha + ps;
;     ...
;   PK4(p0, 0, pa0); PK4(p0, 8, pa1); PK4(p1, 0, pa2); PK4(p1, 8, pa3);
;     ...
; }
; template <int DQK>
; __device__ __forceinline__ void qkt(f32x16& p0, f32x16& p1, const bf16* Ks, const bf16x8* qr, int r32, int hi, int k0, int L) {
;   p0 = f32x16{}; p1 = f32x16{};
; #pragma unroll
;   for (int d0 = 0; d0 < DQK / 16; ++d0) { int cb = (d0 * 16 + hi * 8) * 2;
;     bf16x8 b0 = *reinterpret_cast<const bf16x8*>((const char*)Ks + KSWZ(r32, cb));
;     bf16x8 b1 = *reinterpret_cast<const bf16x8*>((const char*)Ks + KSWZ(32 + r32, cb));
;     p0 = __builtin_amdgcn_mfma_f32_32x32x16_bf16(b0, qr[d0], p0, 0, 0, 0);
;     p1 = __builtin_amdgcn_mfma_f32_32x32x16_bf16(b1, qr[d0], p1, 0, 0, 0); }
;   if (k0 + KVBLK > L) {
; #pragma unroll
;     for (int r = 0; r < 16; ++r) { const int key = k0 + crow(r, hi);
;       if (key >= L) p0[r] = -1e30f;
;       if (key + 32 >= L) p1[r] = -1e30f; }
;   }
; }
; __device__ __forceinline__ int v_st(int k, int c) { const int kk = (k & ~0xC) | ((k & 4) << 1) | ((k & 8) >> 1); return ((kk >> 3) * 4 + (c >> 5)) * 512 + ((kk & 7) * 32 + (c & 31)) * 2; }
; __device__ __forceinline__ int v_rd_base(int lane) { return ((lane & 3) << 3) | (((lane >> 2) & 3) << 6) | (((lane >> 4) & 1) << 5) | (((lane >> 5) & 1) << 8); }
; template <int OFF> __device__ __forceinline__ s16x4 tr_read(int vb) {
;   s16x4 r; asm volatile("ds_read_b64_tr_b16 %0, %1 offset:%2" : "=&v"(r) : "v"(vb), "i"(OFF) : "memory"); return r;
; }
; template <int D0> __device__ __forceinline__ void pv_one(f32x16& od, int vb, bf16x8 pa0, bf16x8 pa1, bf16x8 pa2, bf16x8 pa3) {
;   const s16x4 l0 = tr_read<v_rd_off(D0, 0, 0)>(vb), h0 = tr_read<v_rd_off(D0, 0, 1)>(vb), l1 = tr_read<v_rd_off(D0, 1, 0)>(vb), h1 = tr_read<v_rd_off(D0, 1, 1)>(vb);
.LBB0_842:
	s_or_b64 exec, exec, s[2:3]
	s_barrier
	s_waitcnt vmcnt(2)
	s_waitcnt vmcnt(2)
	ds_write_b128 v160, v[114:117]
	ds_write_b128 v161, v[118:121] offset:32768
	s_waitcnt lgkmcnt(0)
	s_barrier
	s_and_saveexec_b64 s[2:3], s[8:9]
	s_cbranch_execz .LBB0_848
	s_add_i32 s6, s78, 0x80
	s_cmp_le_u32 s6, s79
	s_cbranch_scc0 .Lslow64b
	s_and_b64 vcc, exec, s[10:11]
	s_cbranch_vccz .Lslow64b
	ds_read_b128 v[222:225], v167 offset:32768
	ds_read_b128 v[226:229], v168 offset:32768
	ds_read_b128 v[230:233], v167 offset:40960
	ds_read_b128 v[234:237], v168 offset:40960
	ds_read_b128 v[238:241], v169 offset:32768
	ds_read_b128 v[242:245], v169 offset:40960
	ds_read_b128 v[246:249], v171 offset:32768
	ds_read_b128 v[250:253], v171 offset:40960
	v_cvt_pk_bf16_f32 v130, v66, v67
	v_cvt_pk_bf16_f32 v131, v68, v69
	v_cvt_pk_bf16_f32 v132, v70, v71
	v_cvt_pk_bf16_f32 v133, v72, v73
	v_cvt_pk_bf16_f32 v134, v74, v75
	v_cvt_pk_bf16_f32 v135, v76, v77
	v_cvt_pk_bf16_f32 v136, v78, v79
	v_cvt_pk_bf16_f32 v137, v80, v81
	s_waitcnt lgkmcnt(7)
	v_mfma_f32_32x32x16_bf16 v[50:65], v[222:225], v[98:101], 0
	ds_read_b64_tr_b16 v[186:187], v170 offset:0
	ds_read_b64_tr_b16 v[188:189], v170 offset:2048
	ds_read_b64_tr_b16 v[190:191], v170 offset:4096
	ds_read_b64_tr_b16 v[192:193], v170 offset:6144
	v_permlane32_swap_b32_e32 v130, v132
	v_permlane32_swap_b32_e32 v131, v133
	v_permlane32_swap_b32_e32 v134, v136
	v_permlane32_swap_b32_e32 v135, v137
	s_waitcnt lgkmcnt(10)
	v_mfma_f32_32x32x16_bf16 v[50:65], v[226:229], v[102:105], v[50:65]
	ds_read_b64_tr_b16 v[194:195], v170 offset:8192
	ds_read_b64_tr_b16 v[196:197], v170 offset:10240
	ds_read_b64_tr_b16 v[198:199], v170 offset:12288
	ds_read_b64_tr_b16 v[200:201], v170 offset:14336
	v_exp_f32_e32 v82, v82
	v_exp_f32_e32 v83, v83
	v_exp_f32_e32 v84, v84
	s_waitcnt lgkmcnt(13)
	v_mfma_f32_32x32x16_bf16 v[34:49], v[230:233], v[98:101], 0
	v_exp_f32_e32 v85, v85
	v_exp_f32_e32 v86, v86
	v_exp_f32_e32 v87, v87
	s_waitcnt lgkmcnt(12)
	v_mfma_f32_32x32x16_bf16 v[34:49], v[234:237], v[102:105], v[34:49]
	v_exp_f32_e32 v88, v88
	v_exp_f32_e32 v89, v89
	v_exp_f32_e32 v90, v90
	s_waitcnt lgkmcnt(11)
	v_mfma_f32_32x32x16_bf16 v[50:65], v[238:241], v[106:109], v[50:65]
	v_exp_f32_e32 v91, v91
	v_exp_f32_e32 v92, v92
	v_exp_f32_e32 v93, v93
	s_waitcnt lgkmcnt(10)
	v_mfma_f32_32x32x16_bf16 v[34:49], v[242:245], v[106:109], v[34:49]
	ds_read_b64_tr_b16 v[222:223], v170 offset:512
	ds_read_b64_tr_b16 v[224:225], v170 offset:2560
	ds_read_b64_tr_b16 v[226:227], v170 offset:4608
	ds_read_b64_tr_b16 v[228:229], v170 offset:6656
	v_exp_f32_e32 v94, v94
	v_exp_f32_e32 v95, v95
	v_exp_f32_e32 v96, v96
	s_waitcnt lgkmcnt(13)
	v_mfma_f32_32x32x16_bf16 v[50:65], v[246:249], v[110:113], v[50:65]
	v_exp_f32_e32 v97, v97
	v_cvt_pk_bf16_f32 v138, v82, v83
	v_cvt_pk_bf16_f32 v139, v84, v85
	v_cvt_pk_bf16_f32 v140, v86, v87
	v_cvt_pk_bf16_f32 v141, v88, v89
	s_waitcnt lgkmcnt(12)
	v_mfma_f32_32x32x16_bf16 v[34:49], v[250:253], v[110:113], v[34:49]
	ds_read_b64_tr_b16 v[230:231], v170 offset:8704
	ds_read_b64_tr_b16 v[232:233], v170 offset:10752
	ds_read_b64_tr_b16 v[234:235], v170 offset:12800
	s_waitcnt lgkmcnt(14)
	ds_read_b64_tr_b16 v[236:237], v170 offset:14848
	v_cvt_pk_bf16_f32 v142, v90, v91
	v_cvt_pk_bf16_f32 v143, v92, v93
	v_cvt_pk_bf16_f32 v144, v94, v95
	v_cvt_pk_bf16_f32 v145, v96, v97
	s_nop 0
	v_permlane32_swap_b32_e32 v138, v140
	v_permlane32_swap_b32_e32 v139, v141
	v_permlane32_swap_b32_e32 v142, v144
	v_permlane32_swap_b32_e32 v143, v145
	s_or_b64 exec, exec, s[2:3]
	s_cmp_ge_u32 s73, s97
	s_cselect_b64 s[2:3], -1, 0
	s_and_b64 vcc, exec, s[2:3]
	s_cbranch_vccnz .Lfast64b_nl
	v_add_co_u32_e32 v114, vcc, 0x2ced4000, v152
	s_nop 1
	v_addc_co_u32_e32 v115, vcc, 0, v153, vcc
	v_add_co_u32_e32 v118, vcc, 0x119d0000, v150
	global_load_dwordx4 v[114:117], v[114:115], off offset:2048
	s_nop 0
	v_addc_co_u32_e32 v119, vcc, 0, v151, vcc
	global_load_dwordx4 v[118:121], v[118:119], off
.Lfast64b_nl:
	s_and_saveexec_b64 s[6:7], s[8:9]
	s_waitcnt lgkmcnt(14)
	v_mfma_f32_32x32x16_bf16 v[2:17], v[130:133], v[186:189], v[2:17]
	v_add_f32_e32 v252, 0, v66
	v_add_f32_e32 v252, v67, v252
	v_add_f32_e32 v252, v68, v252
	v_add_f32_e32 v252, v69, v252
	v_exp_f32_e32 v50, v50
	v_exp_f32_e32 v51, v51
	s_waitcnt lgkmcnt(12)
	v_mfma_f32_32x32x16_bf16 v[2:17], v[134:137], v[190:193], v[2:17]
	v_add_f32_e32 v252, v70, v252
	v_add_f32_e32 v252, v71, v252
	v_add_f32_e32 v252, v72, v252
	v_add_f32_e32 v252, v73, v252
	v_exp_f32_e32 v52, v52
	v_exp_f32_e32 v53, v53
	s_waitcnt lgkmcnt(10)
	v_mfma_f32_32x32x16_bf16 v[2:17], v[138:141], v[194:197], v[2:17]
	v_add_f32_e32 v252, v74, v252
	v_add_f32_e32 v252, v75, v252
	v_add_f32_e32 v252, v76, v252
	v_add_f32_e32 v252, v77, v252
	v_exp_f32_e32 v54, v54
	v_exp_f32_e32 v55, v55
	s_waitcnt lgkmcnt(8)
	v_mfma_f32_32x32x16_bf16 v[2:17], v[142:145], v[198:201], v[2:17]
	v_add_f32_e32 v252, v78, v252
	v_add_f32_e32 v252, v79, v252
	v_add_f32_e32 v252, v80, v252
	v_add_f32_e32 v252, v81, v252
	v_exp_f32_e32 v56, v56
	v_exp_f32_e32 v57, v57
	s_waitcnt lgkmcnt(6)
	v_mfma_f32_32x32x16_bf16 v[18:33], v[130:133], v[222:225], v[18:33]
	v_add_f32_e32 v252, v82, v252
	v_add_f32_e32 v252, v83, v252
	v_add_f32_e32 v252, v84, v252
	v_add_f32_e32 v252, v85, v252
	v_exp_f32_e32 v58, v58
	v_exp_f32_e32 v59, v59
	s_waitcnt lgkmcnt(4)
	v_mfma_f32_32x32x16_bf16 v[18:33], v[134:137], v[226:229], v[18:33]
	v_add_f32_e32 v252, v86, v252
	v_add_f32_e32 v252, v87, v252
	v_add_f32_e32 v252, v88, v252
	v_add_f32_e32 v252, v89, v252
	v_exp_f32_e32 v60, v60
	v_exp_f32_e32 v61, v61
	s_waitcnt lgkmcnt(2)
	v_mfma_f32_32x32x16_bf16 v[18:33], v[138:141], v[230:233], v[18:33]
	v_add_f32_e32 v252, v90, v252
	v_add_f32_e32 v252, v91, v252
	v_add_f32_e32 v252, v92, v252
	v_add_f32_e32 v252, v93, v252
	v_exp_f32_e32 v62, v62
	v_exp_f32_e32 v63, v63
	s_waitcnt lgkmcnt(0)
	v_mfma_f32_32x32x16_bf16 v[18:33], v[142:145], v[234:237], v[18:33]
	v_add_f32_e32 v252, v94, v252
	v_add_f32_e32 v252, v95, v252
	v_add_f32_e32 v252, v96, v252
	v_add_f32_e32 v252, v97, v252
	v_exp_f32_e32 v64, v64
	v_exp_f32_e32 v65, v65
	v_mov_b32_e32 v253, v252
	s_nop 1
	v_permlane32_swap_b32_e32 v252, v253
	v_add_f32_e32 v252, v252, v253
	v_add_f32_e32 v163, v163, v252
	s_branch .LBB0_831
; __device__ __forceinline__ int crow(int r, int hi) { return (r & 3) + 8 * (r >> 2) + 4 * hi; }
; template <int DQK>
; __device__ __forceinline__ void qkt(f32x16& p0, f32x16& p1, const bf16* Ks, const bf16x8* qr, int r32, int hi, int k0, int L) {
;   p0 = f32x16{}; p1 = f32x16{};
; #pragma unroll
;   for (int d0 = 0; d0 < DQK / 16; ++d0) { int cb = (d0 * 16 + hi * 8) * 2;
;     bf16x8 b0 = *reinterpret_cast<const bf16x8*>((const char*)Ks + KSWZ(r32, cb));
;     bf16x8 b1 = *reinterpret_cast<const bf16x8*>((const char*)Ks + KSWZ(32 + r32, cb));
;     p0 = __builtin_amdgcn_mfma_f32_32x32x16_bf16(b0, qr[d0], p0, 0, 0, 0);
;     p1 = __builtin_amdgcn_mfma_f32_32x32x16_bf16(b1, qr[d0], p1, 0, 0, 0); }
;   if (k0 + KVBLK > L) {
; #pragma unroll
;     for (int r = 0; r < 16; ++r) { const int key = k0 + crow(r, hi);
;       if (key >= L) p0[r] = -1e30f;
;       if (key + 32 >= L) p1[r] = -1e30f; }
;   }
.Lslow64b:
	ds_read_b128 v[222:225], v167 offset:32768
	ds_read_b128 v[226:229], v168 offset:32768
	ds_read_b128 v[230:233], v167 offset:40960
	ds_read_b128 v[234:237], v168 offset:40960
	ds_read_b128 v[238:241], v169 offset:32768
	ds_read_b128 v[242:245], v169 offset:40960
	ds_read_b128 v[246:249], v171 offset:32768
	ds_read_b128 v[250:253], v171 offset:40960
	s_add_i32 s6, s78, 0x80
	s_cmp_le_u32 s6, s79
	s_waitcnt lgkmcnt(7)
	v_mfma_f32_32x32x16_bf16 v[50:65], v[222:225], v[98:101], 0
	s_waitcnt lgkmcnt(6)
	v_mfma_f32_32x32x16_bf16 v[50:65], v[226:229], v[102:105], v[50:65]
	s_waitcnt lgkmcnt(5)
	v_mfma_f32_32x32x16_bf16 v[34:49], v[230:233], v[98:101], 0
	s_waitcnt lgkmcnt(4)
	v_mfma_f32_32x32x16_bf16 v[34:49], v[234:237], v[102:105], v[34:49]
	s_waitcnt lgkmcnt(3)
	v_mfma_f32_32x32x16_bf16 v[50:65], v[238:241], v[106:109], v[50:65]
	s_waitcnt lgkmcnt(2)
	v_mfma_f32_32x32x16_bf16 v[34:49], v[242:245], v[106:109], v[34:49]
	s_waitcnt lgkmcnt(1)
	v_mfma_f32_32x32x16_bf16 v[50:65], v[246:249], v[110:113], v[50:65]
	s_waitcnt lgkmcnt(0)
	v_mfma_f32_32x32x16_bf16 v[34:49], v[250:253], v[110:113], v[34:49]
	s_cbranch_scc1 .LBB0_847
	v_add_u32_e32 v130, s78, v162
	v_add_u32_e32 v131, 0x80, v130
	v_cmp_gt_u32_e32 vcc, s96, v131
	v_cmp_gt_u32_e64 s[42:43], s72, v131
	v_add_u32_e32 v131, 0x81, v130
	v_cmp_gt_u32_e64 s[12:13], s96, v131
	v_cmp_gt_u32_e64 s[44:45], s72, v131
	v_add_u32_e32 v131, 0x82, v130
	v_cmp_gt_u32_e64 s[14:15], s96, v131
	v_cmp_gt_u32_e64 s[46:47], s72, v131
	v_add_u32_e32 v131, 0x83, v130
	v_cmp_gt_u32_e64 s[16:17], s96, v131
	v_cmp_gt_u32_e64 s[48:49], s72, v131
	v_add_u32_e32 v131, 0x88, v130
	v_cmp_gt_u32_e64 s[18:19], s96, v131
	v_cmp_gt_u32_e64 s[50:51], s72, v131
	v_add_u32_e32 v131, 0x89, v130
	v_cmp_gt_u32_e64 s[20:21], s96, v131
	v_cmp_gt_u32_e64 s[52:53], s72, v131
	v_add_u32_e32 v131, 0x8a, v130
	v_cmp_gt_u32_e64 s[22:23], s96, v131
	v_cmp_gt_u32_e64 s[54:55], s72, v131
	v_add_u32_e32 v131, 0x8b, v130
	v_cmp_gt_u32_e64 s[24:25], s96, v131
	v_cmp_gt_u32_e64 s[56:57], s72, v131
	v_add_u32_e32 v131, 0x90, v130
	v_cmp_gt_u32_e64 s[26:27], s96, v131
	v_cmp_gt_u32_e64 s[58:59], s72, v131
	v_add_u32_e32 v131, 0x91, v130
	v_cmp_gt_u32_e64 s[28:29], s96, v131
	v_cmp_gt_u32_e64 s[60:61], s72, v131
	v_add_u32_e32 v131, 0x92, v130
	v_cmp_gt_u32_e64 s[30:31], s96, v131
	v_cmp_gt_u32_e64 s[62:63], s72, v131
	v_add_u32_e32 v131, 0x93, v130
	v_cmp_gt_u32_e64 s[34:35], s96, v131
	v_cmp_gt_u32_e64 s[64:65], s72, v131
	v_add_u32_e32 v131, 0x98, v130
	v_cmp_gt_u32_e64 s[36:37], s96, v131
	v_cmp_gt_u32_e64 s[66:67], s72, v131
	v_add_u32_e32 v131, 0x99, v130
	v_cmp_gt_u32_e64 s[38:39], s96, v131
	v_cmp_gt_u32_e64 s[68:69], s72, v131
	v_add_u32_e32 v131, 0x9a, v130
	v_cmp_gt_u32_e64 s[70:71], s72, v131
	s_or_b64 s[68:69], s[70:71], s[68:69]
	s_or_b64 s[66:67], s[68:69], s[66:67]
	s_or_b64 s[64:65], s[66:67], s[64:65]
	s_or_b64 s[62:63], s[64:65], s[62:63]
	s_or_b64 s[60:61], s[62:63], s[60:61]
	s_or_b64 s[58:59], s[60:61], s[58:59]
	s_or_b64 s[56:57], s[58:59], s[56:57]
	s_or_b64 s[54:55], s[56:57], s[54:55]
	s_or_b64 s[52:53], s[54:55], s[52:53]
	s_or_b64 s[50:51], s[52:53], s[50:51]
	s_or_b64 s[48:49], s[50:51], s[48:49]
	s_or_b64 s[46:47], s[48:49], s[46:47]
	s_or_b64 s[44:45], s[46:47], s[44:45]
	s_or_b64 s[42:43], s[44:45], s[42:43]
	v_add_u32_e32 v130, 0x9b, v130
	v_cmp_gt_u32_e64 s[40:41], s96, v131
	v_cndmask_b32_e64 v48, v184, v48, s[70:71]
	v_cndmask_b32_e64 v47, v184, v47, s[68:69]
	v_cndmask_b32_e64 v46, v184, v46, s[66:67]
	v_cndmask_b32_e64 v45, v184, v45, s[64:65]
	v_cndmask_b32_e64 v44, v184, v44, s[62:63]
	v_cndmask_b32_e64 v43, v184, v43, s[60:61]
	v_cndmask_b32_e64 v42, v184, v42, s[58:59]
	v_cndmask_b32_e64 v41, v184, v41, s[56:57]
	v_cndmask_b32_e64 v40, v184, v40, s[54:55]
	v_cndmask_b32_e64 v39, v184, v39, s[52:53]
	v_cndmask_b32_e64 v38, v184, v38, s[50:51]
	v_cndmask_b32_e64 v37, v184, v37, s[48:49]
	v_cndmask_b32_e64 v36, v184, v36, s[46:47]
	v_cndmask_b32_e64 v35, v184, v35, s[44:45]
	v_cndmask_b32_e64 v34, v184, v34, s[42:43]
	v_cmp_gt_u32_e64 s[42:43], s96, v130
	v_cmp_le_u32_e64 s[44:45], s72, v130
	s_and_saveexec_b64 s[6:7], s[44:45]
	s_mov_b32 s44, 0xf149f2ca
	v_mov_b32_e32 v49, s44
	s_or_b64 exec, exec, s[6:7]
	s_or_b64 s[40:41], s[42:43], s[40:41]
	s_or_b64 s[38:39], s[40:41], s[38:39]
	s_or_b64 s[36:37], s[38:39], s[36:37]
	s_or_b64 s[34:35], s[36:37], s[34:35]
	s_or_b64 s[30:31], s[34:35], s[30:31]
	s_or_b64 s[28:29], s[30:31], s[28:29]
	s_or_b64 s[26:27], s[28:29], s[26:27]
	s_or_b64 s[24:25], s[26:27], s[24:25]
	s_or_b64 s[22:23], s[24:25], s[22:23]
	s_or_b64 s[20:21], s[22:23], s[20:21]
	s_or_b64 s[18:19], s[20:21], s[18:19]
	s_or_b64 s[16:17], s[18:19], s[16:17]
	s_or_b64 s[14:15], s[16:17], s[14:15]
	s_or_b64 s[12:13], s[14:15], s[12:13]
	s_or_b64 vcc, s[12:13], vcc
	v_cndmask_b32_e64 v64, v184, v64, s[40:41]
	v_cndmask_b32_e64 v63, v184, v63, s[38:39]
	v_cndmask_b32_e64 v62, v184, v62, s[36:37]
	v_cndmask_b32_e64 v61, v184, v61, s[34:35]
	v_cndmask_b32_e64 v60, v184, v60, s[30:31]
	v_cndmask_b32_e64 v59, v184, v59, s[28:29]
	v_cndmask_b32_e64 v58, v184, v58, s[26:27]
	v_cndmask_b32_e64 v57, v184, v57, s[24:25]
	v_cndmask_b32_e64 v56, v184, v56, s[22:23]
	v_cndmask_b32_e64 v55, v184, v55, s[20:21]
	v_cndmask_b32_e64 v54, v184, v54, s[18:19]
	v_cndmask_b32_e64 v53, v184, v53, s[16:17]
	v_cndmask_b32_e64 v52, v184, v52, s[14:15]
	v_cndmask_b32_e64 v51, v184, v51, s[12:13]
	v_cndmask_b32_e32 v50, v184, v50, vcc
	v_cndmask_b32_e64 v65, v184, v65, s[42:43]
	s_movk_i32 s65, 0x600
	s_mov_b64 s[66:67], 0x80
	s_mov_b64 s[68:69], 0x1e90c900

; __device__ __forceinline__ void finishSM(f32x16& p0, f32x16& p1, float alpha, float& l_reg, bf16x8& pa0, bf16x8& pa1, bf16x8& pa2, bf16x8& pa3) {
; #pragma unroll
;   for (int r = 0; r < 16; ++r) p1[r] = __builtin_amdgcn_exp2f(p1[r]);
;   float ps = 0;
; #pragma unroll
;   for (int r = 0; r < 16; ++r) ps += p0[r];
; #pragma unroll
;   for (int r = 0; r < 16; ++r) ps += p1[r];
;   { auto rr = __builtin_amdgcn_permlane32_swap(__float_as_uint(ps), __float_as_uint(ps), false, false);
;     ps = __uint_as_float(rr[0]) + __uint_as_float(rr[1]); }
;   l_reg = l_reg * alpha + ps;
;     ...
;   PK4(p0, 0, pa0); PK4(p0, 8, pa1); PK4(p1, 0, pa2); PK4(p1, 8, pa3);
;     ...
; }
; template <int DQK>
; __device__ __forceinline__ void qkt(f32x16& p0, f32x16& p1, const bf16* Ks, const bf16x8* qr, int r32, int hi, int k0, int L) {
;   p0 = f32x16{}; p1 = f32x16{};
; #pragma unroll
;   for (int d0 = 0; d0 < DQK / 16; ++d0) { int cb = (d0 * 16 + hi * 8) * 2;
;     bf16x8 b0 = *reinterpret_cast<const bf16x8*>((const char*)Ks + KSWZ(r32, cb));
;     bf16x8 b1 = *reinterpret_cast<const bf16x8*>((const char*)Ks + KSWZ(32 + r32, cb));
;     p0 = __builtin_amdgcn_mfma_f32_32x32x16_bf16(b0, qr[d0], p0, 0, 0, 0);
;     p1 = __builtin_amdgcn_mfma_f32_32x32x16_bf16(b1, qr[d0], p1, 0, 0, 0); }
;   if (k0 + KVBLK > L) {
; #pragma unroll
;     for (int r = 0; r < 16; ++r) { const int key = k0 + crow(r, hi);
;       if (key >= L) p0[r] = -1e30f;
;       if (key + 32 >= L) p1[r] = -1e30f; }
;   }
; }
; __device__ __forceinline__ int v_st(int k, int c) { const int kk = (k & ~0xC) | ((k & 4) << 1) | ((k & 8) >> 1); return ((kk >> 3) * 4 + (c >> 5)) * 512 + ((kk & 7) * 32 + (c & 31)) * 2; }
; __device__ __forceinline__ int v_rd_base(int lane) { return ((lane & 3) << 3) | (((lane >> 2) & 3) << 6) | (((lane >> 4) & 1) << 5) | (((lane >> 5) & 1) << 8); }
; template <int OFF> __device__ __forceinline__ s16x4 tr_read(int vb) {
;   s16x4 r; asm volatile("ds_read_b64_tr_b16 %0, %1 offset:%2" : "=&v"(r) : "v"(vb), "i"(OFF) : "memory"); return r;
; }
; template <int D0> __device__ __forceinline__ void pv_one(f32x16& od, int vb, bf16x8 pa0, bf16x8 pa1, bf16x8 pa2, bf16x8 pa3) {
;   const s16x4 l0 = tr_read<v_rd_off(D0, 0, 0)>(vb), h0 = tr_read<v_rd_off(D0, 0, 1)>(vb), l1 = tr_read<v_rd_off(D0, 1, 0)>(vb), h1 = tr_read<v_rd_off(D0, 1, 1)>(vb);
.LBB0_883:
	s_and_saveexec_b64 s[2:3], s[10:11]
	s_cbranch_execz .LBB0_889
	s_add_i32 s14, s4, 64
	s_cmp_le_u32 s14, s5
	s_cbranch_scc0 .Lslow96a
	s_and_b64 vcc, exec, s[12:13]
	s_cbranch_vccz .Lslow96a
	ds_read_b128 v[222:225], v200 offset:49152
	ds_read_b128 v[226:229], v200 offset:57344
	ds_read_b128 v[230:233], v201 offset:49152
	ds_read_b128 v[234:237], v201 offset:57344
	ds_read_b128 v[238:241], v202 offset:49152
	ds_read_b128 v[242:245], v202 offset:57344
	ds_read_b128 v[246:249], v203 offset:49152
	ds_read_b128 v[250:253], v203 offset:57344
	v_cvt_pk_bf16_f32 v10, v64, v65
	v_cvt_pk_bf16_f32 v11, v66, v67
	v_cvt_pk_bf16_f32 v12, v68, v69
	v_cvt_pk_bf16_f32 v13, v70, v71
	v_cvt_pk_bf16_f32 v152, v72, v73
	v_cvt_pk_bf16_f32 v153, v74, v75
	v_cvt_pk_bf16_f32 v154, v76, v77
	v_cvt_pk_bf16_f32 v155, v78, v79
	s_waitcnt lgkmcnt(7)
	v_mfma_f32_32x32x16_bf16 v[80:95], v[222:225], v[112:115], 0
	ds_read_b128 v[222:225], v204 offset:49152
	ds_read_b64_tr_b16 v[206:207], v197 offset:0
	ds_read_b64_tr_b16 v[208:209], v197 offset:2048
	ds_read_b64_tr_b16 v[210:211], v197 offset:4096
	ds_read_b64_tr_b16 v[212:213], v197 offset:6144
	v_permlane32_swap_b32_e32 v10, v12
	v_permlane32_swap_b32_e32 v11, v13
	v_permlane32_swap_b32_e32 v152, v154
	v_permlane32_swap_b32_e32 v153, v155
	s_waitcnt lgkmcnt(11)
	v_mfma_f32_32x32x16_bf16 v[96:111], v[226:229], v[112:115], 0
	ds_read_b128 v[226:229], v204 offset:57344
	ds_read_b64_tr_b16 v[214:215], v197 offset:8192
	ds_read_b64_tr_b16 v[216:217], v197 offset:10240
	ds_read_b64_tr_b16 v[218:219], v197 offset:12288
	s_waitcnt lgkmcnt(14)
	ds_read_b64_tr_b16 v[220:221], v197 offset:14336
	v_exp_f32_e32 v48, v48
	v_exp_f32_e32 v49, v49
	v_mfma_f32_32x32x16_bf16 v[80:95], v[230:233], v[116:119], v[80:95]
	s_waitcnt lgkmcnt(14)
	ds_read_b128 v[230:233], v205 offset:49152
	v_exp_f32_e32 v50, v50
	v_exp_f32_e32 v51, v51
	v_mfma_f32_32x32x16_bf16 v[96:111], v[234:237], v[116:119], v[96:111]
	s_waitcnt lgkmcnt(14)
	ds_read_b128 v[234:237], v205 offset:57344
	v_exp_f32_e32 v52, v52
	v_exp_f32_e32 v53, v53
	v_mfma_f32_32x32x16_bf16 v[80:95], v[238:241], v[120:123], v[80:95]
	v_exp_f32_e32 v54, v54
	v_exp_f32_e32 v55, v55
	s_waitcnt lgkmcnt(14)
	v_mfma_f32_32x32x16_bf16 v[96:111], v[242:245], v[120:123], v[96:111]
	v_exp_f32_e32 v56, v56
	v_exp_f32_e32 v57, v57
	s_waitcnt lgkmcnt(13)
	v_mfma_f32_32x32x16_bf16 v[80:95], v[246:249], v[124:127], v[80:95]
	v_exp_f32_e32 v58, v58
	v_exp_f32_e32 v59, v59
	s_waitcnt lgkmcnt(12)
	v_mfma_f32_32x32x16_bf16 v[96:111], v[250:253], v[124:127], v[96:111]
	v_exp_f32_e32 v60, v60
	v_exp_f32_e32 v61, v61
	s_waitcnt lgkmcnt(11)
	v_mfma_f32_32x32x16_bf16 v[80:95], v[222:225], v[128:131], v[80:95]
	ds_read_b64_tr_b16 v[238:239], v197 offset:512
	ds_read_b64_tr_b16 v[240:241], v197 offset:2560
	ds_read_b64_tr_b16 v[242:243], v197 offset:4608
	ds_read_b64_tr_b16 v[244:245], v197 offset:6656
	v_exp_f32_e32 v62, v62
	v_exp_f32_e32 v63, v63
	s_waitcnt lgkmcnt(10)
	v_mfma_f32_32x32x16_bf16 v[96:111], v[226:229], v[128:131], v[96:111]
	v_cvt_pk_bf16_f32 v156, v48, v49
	v_cvt_pk_bf16_f32 v157, v50, v51
	v_cvt_pk_bf16_f32 v158, v52, v53
	v_cvt_pk_bf16_f32 v159, v54, v55
	s_waitcnt lgkmcnt(5)
	v_mfma_f32_32x32x16_bf16 v[80:95], v[230:233], v[132:135], v[80:95]
	ds_read_b64_tr_b16 v[246:247], v197 offset:8704
	ds_read_b64_tr_b16 v[248:249], v197 offset:10752
	ds_read_b64_tr_b16 v[250:251], v197 offset:12800
	ds_read_b64_tr_b16 v[252:253], v197 offset:14848
	v_cvt_pk_bf16_f32 v160, v56, v57
	v_cvt_pk_bf16_f32 v161, v58, v59
	v_cvt_pk_bf16_f32 v162, v60, v61
	v_cvt_pk_bf16_f32 v163, v62, v63
	s_waitcnt lgkmcnt(8)
	v_mfma_f32_32x32x16_bf16 v[96:111], v[234:237], v[132:135], v[96:111]
	s_nop 0
	v_permlane32_swap_b32_e32 v156, v158
	v_permlane32_swap_b32_e32 v157, v159
	v_permlane32_swap_b32_e32 v160, v162
	v_permlane32_swap_b32_e32 v161, v163
	s_or_b64 exec, exec, s[2:3]
	v_add_co_u32_e32 v2, vcc, 0xffff0000, v170
	v_lshl_add_u64 v[14:15], v[168:169], 0, s[6:7]
	s_nop 0
	v_addc_co_u32_e32 v3, vcc, -1, v171, vcc
	v_add_co_u32_e32 v6, vcc, 0xa148000, v14
	global_load_dwordx4 v[2:5], v[2:3], off
	s_nop 0
	v_addc_co_u32_e32 v7, vcc, 0, v15, vcc
	global_load_dwordx4 v[6:9], v[6:7], off
	s_and_saveexec_b64 s[2:3], s[8:9]
	s_cbranch_execz .Lfast96a_k2
	v_lshl_add_u64 v[140:141], v[166:167], 0, s[6:7]
	v_add_co_u32_e32 v140, vcc, 0xa148000, v140
	s_nop 1
	v_addc_co_u32_e32 v141, vcc, 0, v141, vcc
	global_load_dwordx4 v[140:143], v[140:141], off
.Lfast96a_k2:
	s_or_b64 exec, exec, s[2:3]
	s_and_saveexec_b64 s[2:3], s[10:11]
	v_mfma_f32_32x32x16_bf16 v[32:47], v[10:13], v[206:209], v[32:47]
	v_add_f32_e32 v222, 0, v64
	v_add_f32_e32 v222, v65, v222
	v_add_f32_e32 v222, v66, v222
	v_add_f32_e32 v222, v67, v222
	v_exp_f32_e32 v80, v80
	v_exp_f32_e32 v81, v81
	v_mfma_f32_32x32x16_bf16 v[32:47], v[152:155], v[210:213], v[32:47]
	v_add_f32_e32 v222, v68, v222
	v_add_f32_e32 v222, v69, v222
	v_add_f32_e32 v222, v70, v222
	v_add_f32_e32 v222, v71, v222
	v_exp_f32_e32 v82, v82
	v_exp_f32_e32 v83, v83
	v_mfma_f32_32x32x16_bf16 v[32:47], v[156:159], v[214:217], v[32:47]
	v_add_f32_e32 v222, v72, v222
	v_add_f32_e32 v222, v73, v222
	v_add_f32_e32 v222, v74, v222
	v_add_f32_e32 v222, v75, v222
	v_exp_f32_e32 v84, v84
	v_exp_f32_e32 v85, v85
	v_mfma_f32_32x32x16_bf16 v[32:47], v[160:163], v[218:221], v[32:47]
	v_add_f32_e32 v222, v76, v222
	v_add_f32_e32 v222, v77, v222
	v_add_f32_e32 v222, v78, v222
	v_add_f32_e32 v222, v79, v222
	v_exp_f32_e32 v86, v86
	v_exp_f32_e32 v87, v87
	s_waitcnt lgkmcnt(6)
	v_mfma_f32_32x32x16_bf16 v[16:31], v[10:13], v[238:241], v[16:31]
	v_add_f32_e32 v222, v48, v222
	v_add_f32_e32 v222, v49, v222
	v_add_f32_e32 v222, v50, v222
	v_add_f32_e32 v222, v51, v222
	v_exp_f32_e32 v88, v88
	v_exp_f32_e32 v89, v89
	s_waitcnt lgkmcnt(4)
	v_mfma_f32_32x32x16_bf16 v[16:31], v[152:155], v[242:245], v[16:31]
	v_add_f32_e32 v222, v52, v222
	v_add_f32_e32 v222, v53, v222
	v_add_f32_e32 v222, v54, v222
	v_add_f32_e32 v222, v55, v222
	v_exp_f32_e32 v90, v90
	v_exp_f32_e32 v91, v91
	s_waitcnt lgkmcnt(2)
	v_mfma_f32_32x32x16_bf16 v[16:31], v[156:159], v[246:249], v[16:31]
	v_add_f32_e32 v222, v56, v222
	v_add_f32_e32 v222, v57, v222
	v_add_f32_e32 v222, v58, v222
	v_add_f32_e32 v222, v59, v222
	v_exp_f32_e32 v92, v92
	v_exp_f32_e32 v93, v93
	s_waitcnt lgkmcnt(0)
	v_mfma_f32_32x32x16_bf16 v[16:31], v[160:163], v[250:253], v[16:31]
	v_add_f32_e32 v222, v60, v222
	v_add_f32_e32 v222, v61, v222
	v_add_f32_e32 v222, v62, v222
	v_add_f32_e32 v222, v63, v222
	v_exp_f32_e32 v94, v94
	v_exp_f32_e32 v95, v95
	v_mov_b32_e32 v223, v222
	s_nop 1
	v_permlane32_swap_b32_e32 v222, v223
	v_add_f32_e32 v222, v222, v223
	v_add_f32_e32 v198, v198, v222
	s_branch .LBB0_895
; __device__ __forceinline__ int crow(int r, int hi) { return (r & 3) + 8 * (r >> 2) + 4 * hi; }
; template <int DQK>
; __device__ __forceinline__ void qkt(f32x16& p0, f32x16& p1, const bf16* Ks, const bf16x8* qr, int r32, int hi, int k0, int L) {
;   p0 = f32x16{}; p1 = f32x16{};
; #pragma unroll
;   for (int d0 = 0; d0 < DQK / 16; ++d0) { int cb = (d0 * 16 + hi * 8) * 2;
;     bf16x8 b0 = *reinterpret_cast<const bf16x8*>((const char*)Ks + KSWZ(r32, cb));
;     bf16x8 b1 = *reinterpret_cast<const bf16x8*>((const char*)Ks + KSWZ(32 + r32, cb));
;     p0 = __builtin_amdgcn_mfma_f32_32x32x16_bf16(b0, qr[d0], p0, 0, 0, 0);
;     p1 = __builtin_amdgcn_mfma_f32_32x32x16_bf16(b1, qr[d0], p1, 0, 0, 0); }
;   if (k0 + KVBLK > L) {
; #pragma unroll
;     for (int r = 0; r < 16; ++r) { const int key = k0 + crow(r, hi);
;       if (key >= L) p0[r] = -1e30f;
;       if (key + 32 >= L) p1[r] = -1e30f; }
;   }
.Lslow96a:
	ds_read_b128 v[222:225], v200 offset:49152
	ds_read_b128 v[226:229], v200 offset:57344
	ds_read_b128 v[230:233], v201 offset:49152
	ds_read_b128 v[234:237], v201 offset:57344
	ds_read_b128 v[238:241], v202 offset:49152
	ds_read_b128 v[242:245], v202 offset:57344
	ds_read_b128 v[246:249], v203 offset:49152
	ds_read_b128 v[250:253], v203 offset:57344
	s_add_i32 s14, s4, 64
	s_cmp_le_u32 s14, s5
	s_waitcnt lgkmcnt(7)
	v_mfma_f32_32x32x16_bf16 v[80:95], v[222:225], v[112:115], 0
	ds_read_b128 v[222:225], v204 offset:49152
	s_waitcnt lgkmcnt(7)
	v_mfma_f32_32x32x16_bf16 v[96:111], v[226:229], v[112:115], 0
	ds_read_b128 v[226:229], v204 offset:57344
	s_waitcnt lgkmcnt(7)
	v_mfma_f32_32x32x16_bf16 v[80:95], v[230:233], v[116:119], v[80:95]
	ds_read_b128 v[230:233], v205 offset:49152
	s_waitcnt lgkmcnt(7)
	v_mfma_f32_32x32x16_bf16 v[96:111], v[234:237], v[116:119], v[96:111]
	ds_read_b128 v[234:237], v205 offset:57344
	s_waitcnt lgkmcnt(7)
	v_mfma_f32_32x32x16_bf16 v[80:95], v[238:241], v[120:123], v[80:95]
	s_waitcnt lgkmcnt(6)
	v_mfma_f32_32x32x16_bf16 v[96:111], v[242:245], v[120:123], v[96:111]
	s_waitcnt lgkmcnt(5)
	v_mfma_f32_32x32x16_bf16 v[80:95], v[246:249], v[124:127], v[80:95]
	s_waitcnt lgkmcnt(4)
	v_mfma_f32_32x32x16_bf16 v[96:111], v[250:253], v[124:127], v[96:111]
	s_waitcnt lgkmcnt(3)
	v_mfma_f32_32x32x16_bf16 v[80:95], v[222:225], v[128:131], v[80:95]
	s_waitcnt lgkmcnt(2)
	v_mfma_f32_32x32x16_bf16 v[96:111], v[226:229], v[128:131], v[96:111]
	s_waitcnt lgkmcnt(1)
	v_mfma_f32_32x32x16_bf16 v[80:95], v[230:233], v[132:135], v[80:95]
	s_waitcnt lgkmcnt(0)
	v_mfma_f32_32x32x16_bf16 v[96:111], v[234:237], v[132:135], v[96:111]
	s_cbranch_scc1 .LBB0_888
	v_add_u32_e32 v0, s4, v196
	v_add_u32_e32 v2, 64, v0
	v_cmp_gt_u32_e32 vcc, s96, v2
	v_cmp_gt_u32_e64 s[44:45], s78, v2
	v_add_u32_e32 v2, 0x41, v0
	v_cmp_gt_u32_e64 s[14:15], s96, v2
	v_cmp_gt_u32_e64 s[46:47], s78, v2
	v_add_u32_e32 v2, 0x42, v0
	v_cmp_gt_u32_e64 s[16:17], s96, v2
	v_cmp_gt_u32_e64 s[48:49], s78, v2
	v_add_u32_e32 v2, 0x43, v0
	v_cmp_gt_u32_e64 s[18:19], s96, v2
	v_cmp_gt_u32_e64 s[50:51], s78, v2
	v_add_u32_e32 v2, 0x48, v0
	v_cmp_gt_u32_e64 s[20:21], s96, v2
	v_cmp_gt_u32_e64 s[52:53], s78, v2
	v_add_u32_e32 v2, 0x49, v0
	v_cmp_gt_u32_e64 s[22:23], s96, v2
	v_cmp_gt_u32_e64 s[54:55], s78, v2
	v_add_u32_e32 v2, 0x4a, v0
	v_cmp_gt_u32_e64 s[24:25], s96, v2
	v_cmp_gt_u32_e64 s[56:57], s78, v2
	v_add_u32_e32 v2, 0x4b, v0
	v_cmp_gt_u32_e64 s[26:27], s96, v2
	v_cmp_gt_u32_e64 s[58:59], s78, v2
	v_add_u32_e32 v2, 0x50, v0
	v_cmp_gt_u32_e64 s[28:29], s96, v2
	v_cmp_gt_u32_e64 s[60:61], s78, v2
	v_add_u32_e32 v2, 0x51, v0
	v_cmp_gt_u32_e64 s[30:31], s96, v2
	v_cmp_gt_u32_e64 s[62:63], s78, v2
	v_add_u32_e32 v2, 0x52, v0
	v_cmp_gt_u32_e64 s[34:35], s96, v2
	v_cmp_gt_u32_e64 s[64:65], s78, v2
	v_add_u32_e32 v2, 0x53, v0
	v_cmp_gt_u32_e64 s[36:37], s96, v2
	v_cmp_gt_u32_e64 s[66:67], s78, v2
	v_add_u32_e32 v2, 0x58, v0
	v_cmp_gt_u32_e64 s[38:39], s96, v2
	v_cmp_gt_u32_e64 s[68:69], s78, v2
	v_add_u32_e32 v2, 0x59, v0
	v_cmp_gt_u32_e64 s[40:41], s96, v2
	v_cmp_gt_u32_e64 s[70:71], s78, v2
	v_add_u32_e32 v2, 0x5a, v0
	v_cmp_gt_u32_e64 s[72:73], s78, v2
	s_or_b64 s[70:71], s[72:73], s[70:71]
	s_or_b64 s[68:69], s[70:71], s[68:69]
	s_or_b64 s[66:67], s[68:69], s[66:67]
	s_or_b64 s[64:65], s[66:67], s[64:65]
	s_or_b64 s[62:63], s[64:65], s[62:63]
	s_or_b64 s[60:61], s[62:63], s[60:61]
	s_or_b64 s[58:59], s[60:61], s[58:59]
	s_or_b64 s[56:57], s[58:59], s[56:57]
	s_or_b64 s[54:55], s[56:57], s[54:55]
	s_or_b64 s[52:53], s[54:55], s[52:53]
	s_or_b64 s[50:51], s[52:53], s[50:51]
	s_or_b64 s[48:49], s[50:51], s[48:49]
	s_or_b64 s[46:47], s[48:49], s[46:47]
	s_or_b64 s[44:45], s[46:47], s[44:45]
	v_add_u32_e32 v0, 0x5b, v0
	v_cmp_gt_u32_e64 s[42:43], s96, v2
	v_cndmask_b32_e64 v110, v184, v110, s[72:73]
	v_cndmask_b32_e64 v109, v184, v109, s[70:71]
	v_cndmask_b32_e64 v108, v184, v108, s[68:69]
	v_cndmask_b32_e64 v107, v184, v107, s[66:67]
	v_cndmask_b32_e64 v106, v184, v106, s[64:65]
	v_cndmask_b32_e64 v105, v184, v105, s[62:63]
	v_cndmask_b32_e64 v104, v184, v104, s[60:61]
	v_cndmask_b32_e64 v103, v184, v103, s[58:59]
	v_cndmask_b32_e64 v102, v184, v102, s[56:57]
	v_cndmask_b32_e64 v101, v184, v101, s[54:55]
	v_cndmask_b32_e64 v100, v184, v100, s[52:53]
	v_cndmask_b32_e64 v99, v184, v99, s[50:51]
	v_cndmask_b32_e64 v98, v184, v98, s[48:49]
	v_cndmask_b32_e64 v97, v184, v97, s[46:47]
	v_cndmask_b32_e64 v96, v184, v96, s[44:45]
	v_cmp_gt_u32_e64 s[44:45], s96, v0
	v_cmp_le_u32_e64 s[46:47], s78, v0
	s_and_saveexec_b64 s[48:49], s[46:47]
	s_mov_b32 s46, 0xf149f2ca
	v_mov_b32_e32 v111, s46
	s_or_b64 exec, exec, s[48:49]
	s_or_b64 s[42:43], s[44:45], s[42:43]
	s_or_b64 s[40:41], s[42:43], s[40:41]
	s_or_b64 s[38:39], s[40:41], s[38:39]
	s_or_b64 s[36:37], s[38:39], s[36:37]
	s_or_b64 s[34:35], s[36:37], s[34:35]
	s_or_b64 s[30:31], s[34:35], s[30:31]
	s_or_b64 s[28:29], s[30:31], s[28:29]
	s_or_b64 s[26:27], s[28:29], s[26:27]
	s_or_b64 s[24:25], s[26:27], s[24:25]
	s_or_b64 s[22:23], s[24:25], s[22:23]
	s_or_b64 s[20:21], s[22:23], s[20:21]
	s_or_b64 s[18:19], s[20:21], s[18:19]
	s_or_b64 s[16:17], s[18:19], s[16:17]
	s_or_b64 s[14:15], s[16:17], s[14:15]
	s_or_b64 vcc, s[14:15], vcc
	v_cndmask_b32_e64 v94, v184, v94, s[42:43]
	v_cndmask_b32_e64 v93, v184, v93, s[40:41]
	v_cndmask_b32_e64 v92, v184, v92, s[38:39]
	v_cndmask_b32_e64 v91, v184, v91, s[36:37]
	v_cndmask_b32_e64 v90, v184, v90, s[34:35]
	v_cndmask_b32_e64 v89, v184, v89, s[30:31]
	v_cndmask_b32_e64 v88, v184, v88, s[28:29]
	v_cndmask_b32_e64 v87, v184, v87, s[26:27]
	v_cndmask_b32_e64 v86, v184, v86, s[24:25]
	v_cndmask_b32_e64 v85, v184, v85, s[22:23]
	v_cndmask_b32_e64 v84, v184, v84, s[20:21]
	v_cndmask_b32_e64 v83, v184, v83, s[18:19]
	v_cndmask_b32_e64 v82, v184, v82, s[16:17]
	v_cndmask_b32_e64 v81, v184, v81, s[14:15]
	v_cndmask_b32_e32 v80, v184, v80, vcc
	v_cndmask_b32_e64 v95, v184, v95, s[44:45]
	s_movk_i32 s65, 0x600
	s_mov_b64 s[66:67], 0x80
	s_mov_b64 s[68:69], 0x1e90c900

; __device__ __forceinline__ void finishSM(f32x16& p0, f32x16& p1, float alpha, float& l_reg, bf16x8& pa0, bf16x8& pa1, bf16x8& pa2, bf16x8& pa3) {
; #pragma unroll
;   for (int r = 0; r < 16; ++r) p1[r] = __builtin_amdgcn_exp2f(p1[r]);
;   float ps = 0;
; #pragma unroll
;   for (int r = 0; r < 16; ++r) ps += p0[r];
; #pragma unroll
;   for (int r = 0; r < 16; ++r) ps += p1[r];
;   { auto rr = __builtin_amdgcn_permlane32_swap(__float_as_uint(ps), __float_as_uint(ps), false, false);
;     ps = __uint_as_float(rr[0]) + __uint_as_float(rr[1]); }
;   l_reg = l_reg * alpha + ps;
;     ...
;   PK4(p0, 0, pa0); PK4(p0, 8, pa1); PK4(p1, 0, pa2); PK4(p1, 8, pa3);
;     ...
; }
; template <int DQK>
; __device__ __forceinline__ void qkt(f32x16& p0, f32x16& p1, const bf16* Ks, const bf16x8* qr, int r32, int hi, int k0, int L) {
;   p0 = f32x16{}; p1 = f32x16{};
; #pragma unroll
;   for (int d0 = 0; d0 < DQK / 16; ++d0) { int cb = (d0 * 16 + hi * 8) * 2;
;     bf16x8 b0 = *reinterpret_cast<const bf16x8*>((const char*)Ks + KSWZ(r32, cb));
;     bf16x8 b1 = *reinterpret_cast<const bf16x8*>((const char*)Ks + KSWZ(32 + r32, cb));
;     p0 = __builtin_amdgcn_mfma_f32_32x32x16_bf16(b0, qr[d0], p0, 0, 0, 0);
;     p1 = __builtin_amdgcn_mfma_f32_32x32x16_bf16(b1, qr[d0], p1, 0, 0, 0); }
;   if (k0 + KVBLK > L) {
; #pragma unroll
;     for (int r = 0; r < 16; ++r) { const int key = k0 + crow(r, hi);
;       if (key >= L) p0[r] = -1e30f;
;       if (key + 32 >= L) p1[r] = -1e30f; }
;   }
; }
; __device__ __forceinline__ int v_st(int k, int c) { const int kk = (k & ~0xC) | ((k & 4) << 1) | ((k & 8) >> 1); return ((kk >> 3) * 4 + (c >> 5)) * 512 + ((kk & 7) * 32 + (c & 31)) * 2; }
; __device__ __forceinline__ int v_rd_base(int lane) { return ((lane & 3) << 3) | (((lane >> 2) & 3) << 6) | (((lane >> 4) & 1) << 5) | (((lane >> 5) & 1) << 8); }
; template <int OFF> __device__ __forceinline__ s16x4 tr_read(int vb) {
;   s16x4 r; asm volatile("ds_read_b64_tr_b16 %0, %1 offset:%2" : "=&v"(r) : "v"(vb), "i"(OFF) : "memory"); return r;
; }
; template <int D0> __device__ __forceinline__ void pv_one(f32x16& od, int vb, bf16x8 pa0, bf16x8 pa1, bf16x8 pa2, bf16x8 pa3) {
;   const s16x4 l0 = tr_read<v_rd_off(D0, 0, 0)>(vb), h0 = tr_read<v_rd_off(D0, 0, 1)>(vb), l1 = tr_read<v_rd_off(D0, 1, 0)>(vb), h1 = tr_read<v_rd_off(D0, 1, 1)>(vb);
.LBB0_895:
	s_or_b64 exec, exec, s[2:3]
	s_barrier
	s_waitcnt vmcnt(2)
	s_waitcnt vmcnt(3)
	ds_write_b128 v193, v[144:147]
	s_waitcnt vmcnt(2)
	ds_write_b128 v194, v[148:151] offset:32768
	s_and_saveexec_b64 s[2:3], s[8:9]
	ds_write_b128 v195, v[136:139] offset:32768
	s_or_b64 exec, exec, s[2:3]
	s_waitcnt lgkmcnt(0)
	s_barrier
	s_and_saveexec_b64 s[2:3], s[10:11]
	s_cbranch_execz .LBB0_903
	s_add_i32 s14, s4, 0x80
	s_cmp_le_u32 s14, s5
	s_cbranch_scc0 .Lslow96b
	s_and_b64 vcc, exec, s[12:13]
	s_cbranch_vccz .Lslow96b
	ds_read_b128 v[222:225], v200 offset:32768
	ds_read_b128 v[226:229], v200 offset:40960
	ds_read_b128 v[230:233], v201 offset:32768
	ds_read_b128 v[234:237], v201 offset:40960
	ds_read_b128 v[238:241], v202 offset:32768
	ds_read_b128 v[242:245], v202 offset:40960
	ds_read_b128 v[246:249], v203 offset:32768
	ds_read_b128 v[250:253], v203 offset:40960
	v_cvt_pk_bf16_f32 v10, v80, v81
	v_cvt_pk_bf16_f32 v11, v82, v83
	v_cvt_pk_bf16_f32 v12, v84, v85
	v_cvt_pk_bf16_f32 v13, v86, v87
	v_cvt_pk_bf16_f32 v152, v88, v89
	v_cvt_pk_bf16_f32 v153, v90, v91
	v_cvt_pk_bf16_f32 v154, v92, v93
	v_cvt_pk_bf16_f32 v155, v94, v95
	s_waitcnt lgkmcnt(7)
	v_mfma_f32_32x32x16_bf16 v[64:79], v[222:225], v[112:115], 0
	ds_read_b128 v[222:225], v204 offset:32768
	ds_read_b64_tr_b16 v[206:207], v199 offset:0
	ds_read_b64_tr_b16 v[208:209], v199 offset:2048
	ds_read_b64_tr_b16 v[210:211], v199 offset:4096
	ds_read_b64_tr_b16 v[212:213], v199 offset:6144
	v_permlane32_swap_b32_e32 v10, v12
	v_permlane32_swap_b32_e32 v11, v13
	v_permlane32_swap_b32_e32 v152, v154
	v_permlane32_swap_b32_e32 v153, v155
	s_waitcnt lgkmcnt(11)
	v_mfma_f32_32x32x16_bf16 v[48:63], v[226:229], v[112:115], 0
	ds_read_b128 v[226:229], v204 offset:40960
	ds_read_b64_tr_b16 v[214:215], v199 offset:8192
	ds_read_b64_tr_b16 v[216:217], v199 offset:10240
	ds_read_b64_tr_b16 v[218:219], v199 offset:12288
	s_waitcnt lgkmcnt(14)
	ds_read_b64_tr_b16 v[220:221], v199 offset:14336
	v_exp_f32_e32 v96, v96
	v_exp_f32_e32 v97, v97
	v_mfma_f32_32x32x16_bf16 v[64:79], v[230:233], v[116:119], v[64:79]
	s_waitcnt lgkmcnt(14)
	ds_read_b128 v[230:233], v205 offset:32768
	v_exp_f32_e32 v98, v98
	v_exp_f32_e32 v99, v99
	v_mfma_f32_32x32x16_bf16 v[48:63], v[234:237], v[116:119], v[48:63]
	s_waitcnt lgkmcnt(14)
	ds_read_b128 v[234:237], v205 offset:40960
	v_exp_f32_e32 v100, v100
	v_exp_f32_e32 v101, v101
	v_mfma_f32_32x32x16_bf16 v[64:79], v[238:241], v[120:123], v[64:79]
	v_exp_f32_e32 v102, v102
	v_exp_f32_e32 v103, v103
	s_waitcnt lgkmcnt(14)
	v_mfma_f32_32x32x16_bf16 v[48:63], v[242:245], v[120:123], v[48:63]
	v_exp_f32_e32 v104, v104
	v_exp_f32_e32 v105, v105
	s_waitcnt lgkmcnt(13)
	v_mfma_f32_32x32x16_bf16 v[64:79], v[246:249], v[124:127], v[64:79]
	v_exp_f32_e32 v106, v106
	v_exp_f32_e32 v107, v107
	s_waitcnt lgkmcnt(12)
	v_mfma_f32_32x32x16_bf16 v[48:63], v[250:253], v[124:127], v[48:63]
	v_exp_f32_e32 v108, v108
	v_exp_f32_e32 v109, v109
	s_waitcnt lgkmcnt(11)
	v_mfma_f32_32x32x16_bf16 v[64:79], v[222:225], v[128:131], v[64:79]
	ds_read_b64_tr_b16 v[238:239], v199 offset:512
	ds_read_b64_tr_b16 v[240:241], v199 offset:2560
	ds_read_b64_tr_b16 v[242:243], v199 offset:4608
	ds_read_b64_tr_b16 v[244:245], v199 offset:6656
	v_exp_f32_e32 v110, v110
	v_exp_f32_e32 v111, v111
	s_waitcnt lgkmcnt(10)
	v_mfma_f32_32x32x16_bf16 v[48:63], v[226:229], v[128:131], v[48:63]
	v_cvt_pk_bf16_f32 v156, v96, v97
	v_cvt_pk_bf16_f32 v157, v98, v99
	v_cvt_pk_bf16_f32 v158, v100, v101
	v_cvt_pk_bf16_f32 v159, v102, v103
	s_waitcnt lgkmcnt(5)
	v_mfma_f32_32x32x16_bf16 v[64:79], v[230:233], v[132:135], v[64:79]
	ds_read_b64_tr_b16 v[246:247], v199 offset:8704
	ds_read_b64_tr_b16 v[248:249], v199 offset:10752
	ds_read_b64_tr_b16 v[250:251], v199 offset:12800
	ds_read_b64_tr_b16 v[252:253], v199 offset:14848
	v_cvt_pk_bf16_f32 v160, v104, v105
	v_cvt_pk_bf16_f32 v161, v106, v107
	v_cvt_pk_bf16_f32 v162, v108, v109
	v_cvt_pk_bf16_f32 v163, v110, v111
	s_waitcnt lgkmcnt(8)
	v_mfma_f32_32x32x16_bf16 v[48:63], v[234:237], v[132:135], v[48:63]
	s_nop 0
	v_permlane32_swap_b32_e32 v156, v158
	v_permlane32_swap_b32_e32 v157, v159
	v_permlane32_swap_b32_e32 v160, v162
	v_permlane32_swap_b32_e32 v161, v163
	s_or_b64 exec, exec, s[2:3]
	s_cmp_ge_u32 s79, s97
	s_cselect_b64 s[2:3], -1, 0
	s_and_b64 vcc, exec, s[2:3]
	s_cbranch_vccnz .Lfast96b_nl
	v_add_co_u32_e32 v14, vcc, 0xa160000, v14
	global_load_dwordx4 v[144:147], v[170:171], off
	s_nop 0
	v_addc_co_u32_e32 v15, vcc, 0, v15, vcc
	global_load_dwordx4 v[148:151], v[14:15], off
	s_and_saveexec_b64 s[14:15], s[8:9]
	s_cbranch_execz .Lfast96b_k2
	v_lshl_add_u64 v[14:15], v[166:167], 0, s[6:7]
	v_add_co_u32_e32 v14, vcc, 0xa160000, v14
	s_nop 1
	v_addc_co_u32_e32 v15, vcc, 0, v15, vcc
	global_load_dwordx4 v[136:139], v[14:15], off

; template <int DQK, bool FIX>
; __device__ __forceinline__ void partialSM(f32x16& p0, f32x16& p1, float& m_reg, float& mn, float& alpha, float mC) {
;     ...
;   for (int r = 0; r < 16; ++r) p0[r] = __builtin_amdgcn_exp2f(p0[r]);
; }
; __device__ __forceinline__ void finishSM(f32x16& p0, f32x16& p1, float alpha, float& l_reg, bf16x8& pa0, bf16x8& pa1, bf16x8& pa2, bf16x8& pa3) {
; #pragma unroll
;   for (int r = 0; r < 16; ++r) p1[r] = __builtin_amdgcn_exp2f(p1[r]);
;   float ps = 0;
; #pragma unroll
;   for (int r = 0; r < 16; ++r) ps += p0[r];
; #pragma unroll
;   for (int r = 0; r < 16; ++r) ps += p1[r];
;   { auto rr = __builtin_amdgcn_permlane32_swap(__float_as_uint(ps), __float_as_uint(ps), false, false);
;     ps = __uint_as_float(rr[0]) + __uint_as_float(rr[1]); }
;   l_reg = l_reg * alpha + ps;
;     ...
;   PK4(p0, 0, pa0); PK4(p0, 8, pa1); PK4(p1, 0, pa2); PK4(p1, 8, pa3);
;     ...
; }
; template <int DQK>
; __device__ __forceinline__ void qkt(f32x16& p0, f32x16& p1, const bf16* Ks, const bf16x8* qr, int r32, int hi, int k0, int L) {
;   p0 = f32x16{}; p1 = f32x16{};
; #pragma unroll
;   for (int d0 = 0; d0 < DQK / 16; ++d0) { int cb = (d0 * 16 + hi * 8) * 2;
;     bf16x8 b0 = *reinterpret_cast<const bf16x8*>((const char*)Ks + KSWZ(r32, cb));
;     bf16x8 b1 = *reinterpret_cast<const bf16x8*>((const char*)Ks + KSWZ(32 + r32, cb));
;     p0 = __builtin_amdgcn_mfma_f32_32x32x16_bf16(b0, qr[d0], p0, 0, 0, 0);
;     p1 = __builtin_amdgcn_mfma_f32_32x32x16_bf16(b1, qr[d0], p1, 0, 0, 0); }
;   if (k0 + KVBLK > L) {
; #pragma unroll
;     for (int r = 0; r < 16; ++r) { const int key = k0 + crow(r, hi);
;       if (key >= L) p0[r] = -1e30f;
;       if (key + 32 >= L) p1[r] = -1e30f; }
;   }
; }
; __device__ __forceinline__ int v_st(int k, int c) { const int kk = (k & ~0xC) | ((k & 4) << 1) | ((k & 8) >> 1); return ((kk >> 3) * 4 + (c >> 5)) * 512 + ((kk & 7) * 32 + (c & 31)) * 2; }
; __device__ __forceinline__ int v_rd_base(int lane) { return ((lane & 3) << 3) | (((lane >> 2) & 3) << 6) | (((lane >> 4) & 1) << 5) | (((lane >> 5) & 1) << 8); }
; template <int OFF> __device__ __forceinline__ s16x4 tr_read(int vb) {
;   s16x4 r; asm volatile("ds_read_b64_tr_b16 %0, %1 offset:%2" : "=&v"(r) : "v"(vb), "i"(OFF) : "memory"); return r;
; }
; template <int D0> __device__ __forceinline__ void pv_one(f32x16& od, int vb, bf16x8 pa0, bf16x8 pa1, bf16x8 pa2, bf16x8 pa3) {
.Lfast96b_nl:
	s_and_saveexec_b64 s[14:15], s[10:11]
	v_mfma_f32_32x32x16_bf16 v[32:47], v[10:13], v[206:209], v[32:47]
	v_add_f32_e32 v222, 0, v80
	v_add_f32_e32 v222, v81, v222
	v_add_f32_e32 v222, v82, v222
	v_add_f32_e32 v222, v83, v222
	v_exp_f32_e32 v64, v64
	v_exp_f32_e32 v65, v65
	v_mfma_f32_32x32x16_bf16 v[32:47], v[152:155], v[210:213], v[32:47]
	v_add_f32_e32 v222, v84, v222
	v_add_f32_e32 v222, v85, v222
	v_add_f32_e32 v222, v86, v222
	v_add_f32_e32 v222, v87, v222
	v_exp_f32_e32 v66, v66
	v_exp_f32_e32 v67, v67
	v_mfma_f32_32x32x16_bf16 v[32:47], v[156:159], v[214:217], v[32:47]
	v_add_f32_e32 v222, v88, v222
	v_add_f32_e32 v222, v89, v222
	v_add_f32_e32 v222, v90, v222
	v_add_f32_e32 v222, v91, v222
	v_exp_f32_e32 v68, v68
	v_exp_f32_e32 v69, v69
	v_mfma_f32_32x32x16_bf16 v[32:47], v[160:163], v[218:221], v[32:47]
	v_add_f32_e32 v222, v92, v222
	v_add_f32_e32 v222, v93, v222
	v_add_f32_e32 v222, v94, v222
	v_add_f32_e32 v222, v95, v222
	v_exp_f32_e32 v70, v70
	v_exp_f32_e32 v71, v71
	s_waitcnt lgkmcnt(6)
	v_mfma_f32_32x32x16_bf16 v[16:31], v[10:13], v[238:241], v[16:31]
	v_add_f32_e32 v222, v96, v222
	v_add_f32_e32 v222, v97, v222
	v_add_f32_e32 v222, v98, v222
	v_add_f32_e32 v222, v99, v222
	v_exp_f32_e32 v72, v72
	v_exp_f32_e32 v73, v73
	s_waitcnt lgkmcnt(4)
	v_mfma_f32_32x32x16_bf16 v[16:31], v[152:155], v[242:245], v[16:31]
	v_add_f32_e32 v222, v100, v222
	v_add_f32_e32 v222, v101, v222
	v_add_f32_e32 v222, v102, v222
	v_add_f32_e32 v222, v103, v222
	v_exp_f32_e32 v74, v74
	v_exp_f32_e32 v75, v75
	s_waitcnt lgkmcnt(2)
	v_mfma_f32_32x32x16_bf16 v[16:31], v[156:159], v[246:249], v[16:31]
	v_add_f32_e32 v222, v104, v222
	v_add_f32_e32 v222, v105, v222
	v_add_f32_e32 v222, v106, v222
	v_add_f32_e32 v222, v107, v222
	v_exp_f32_e32 v76, v76
	v_exp_f32_e32 v77, v77
	s_waitcnt lgkmcnt(0)
	v_mfma_f32_32x32x16_bf16 v[16:31], v[160:163], v[250:253], v[16:31]
	v_add_f32_e32 v222, v108, v222
	v_add_f32_e32 v222, v109, v222
	v_add_f32_e32 v222, v110, v222
	v_add_f32_e32 v222, v111, v222
	v_exp_f32_e32 v78, v78
	v_exp_f32_e32 v79, v79
	v_mov_b32_e32 v223, v222
	s_nop 1
	v_permlane32_swap_b32_e32 v222, v223
	v_add_f32_e32 v222, v222, v223
	v_add_f32_e32 v198, v198, v222
	s_branch .LBB0_911
; __device__ __forceinline__ int crow(int r, int hi) { return (r & 3) + 8 * (r >> 2) + 4 * hi; }
; template <int DQK>
; __device__ __forceinline__ void qkt(f32x16& p0, f32x16& p1, const bf16* Ks, const bf16x8* qr, int r32, int hi, int k0, int L) {
;   p0 = f32x16{}; p1 = f32x16{};
; #pragma unroll
;   for (int d0 = 0; d0 < DQK / 16; ++d0) { int cb = (d0 * 16 + hi * 8) * 2;
;     bf16x8 b0 = *reinterpret_cast<const bf16x8*>((const char*)Ks + KSWZ(r32, cb));
;     bf16x8 b1 = *reinterpret_cast<const bf16x8*>((const char*)Ks + KSWZ(32 + r32, cb));
;     p0 = __builtin_amdgcn_mfma_f32_32x32x16_bf16(b0, qr[d0], p0, 0, 0, 0);
;     p1 = __builtin_amdgcn_mfma_f32_32x32x16_bf16(b1, qr[d0], p1, 0, 0, 0); }
;   if (k0 + KVBLK > L) {
; #pragma unroll
;     for (int r = 0; r < 16; ++r) { const int key = k0 + crow(r, hi);
;       if (key >= L) p0[r] = -1e30f;
;       if (key + 32 >= L) p1[r] = -1e30f; }
;   }
.Lslow96b:
	ds_read_b128 v[222:225], v200 offset:32768
	ds_read_b128 v[226:229], v200 offset:40960
	ds_read_b128 v[230:233], v201 offset:32768
	ds_read_b128 v[234:237], v201 offset:40960
	ds_read_b128 v[238:241], v202 offset:32768
	ds_read_b128 v[242:245], v202 offset:40960
	ds_read_b128 v[246:249], v203 offset:32768
	ds_read_b128 v[250:253], v203 offset:40960
	s_add_i32 s14, s4, 0x80
	s_cmp_le_u32 s14, s5
	s_waitcnt lgkmcnt(7)
	v_mfma_f32_32x32x16_bf16 v[64:79], v[222:225], v[112:115], 0
	ds_read_b128 v[222:225], v204 offset:32768
	s_waitcnt lgkmcnt(7)
	v_mfma_f32_32x32x16_bf16 v[48:63], v[226:229], v[112:115], 0
	ds_read_b128 v[226:229], v204 offset:40960
	s_waitcnt lgkmcnt(7)
	v_mfma_f32_32x32x16_bf16 v[64:79], v[230:233], v[116:119], v[64:79]
	ds_read_b128 v[230:233], v205 offset:32768
	s_waitcnt lgkmcnt(7)
	v_mfma_f32_32x32x16_bf16 v[48:63], v[234:237], v[116:119], v[48:63]
	ds_read_b128 v[234:237], v205 offset:40960
	s_waitcnt lgkmcnt(7)
	v_mfma_f32_32x32x16_bf16 v[64:79], v[238:241], v[120:123], v[64:79]
	s_waitcnt lgkmcnt(6)
	v_mfma_f32_32x32x16_bf16 v[48:63], v[242:245], v[120:123], v[48:63]
	s_waitcnt lgkmcnt(5)
	v_mfma_f32_32x32x16_bf16 v[64:79], v[246:249], v[124:127], v[64:79]
	s_waitcnt lgkmcnt(4)
	v_mfma_f32_32x32x16_bf16 v[48:63], v[250:253], v[124:127], v[48:63]
	s_waitcnt lgkmcnt(3)
	v_mfma_f32_32x32x16_bf16 v[64:79], v[222:225], v[128:131], v[64:79]
	s_waitcnt lgkmcnt(2)
	v_mfma_f32_32x32x16_bf16 v[48:63], v[226:229], v[128:131], v[48:63]
	s_waitcnt lgkmcnt(1)
	v_mfma_f32_32x32x16_bf16 v[64:79], v[230:233], v[132:135], v[64:79]
	s_waitcnt lgkmcnt(0)
	v_mfma_f32_32x32x16_bf16 v[48:63], v[234:237], v[132:135], v[48:63]
	s_cbranch_scc1 .LBB0_902
	v_add_u32_e32 v0, s4, v196
	v_add_u32_e32 v10, 0x80, v0
	v_cmp_gt_u32_e32 vcc, s96, v10
	v_cmp_gt_u32_e64 s[44:45], s78, v10
	v_add_u32_e32 v10, 0x81, v0
	v_cmp_gt_u32_e64 s[14:15], s96, v10
	v_cmp_gt_u32_e64 s[46:47], s78, v10
	v_add_u32_e32 v10, 0x82, v0
	v_cmp_gt_u32_e64 s[16:17], s96, v10
	v_cmp_gt_u32_e64 s[48:49], s78, v10
	v_add_u32_e32 v10, 0x83, v0
	v_cmp_gt_u32_e64 s[18:19], s96, v10
	v_cmp_gt_u32_e64 s[50:51], s78, v10
	v_add_u32_e32 v10, 0x88, v0
	v_cmp_gt_u32_e64 s[20:21], s96, v10
	v_cmp_gt_u32_e64 s[52:53], s78, v10
	v_add_u32_e32 v10, 0x89, v0
	v_cmp_gt_u32_e64 s[22:23], s96, v10
	v_cmp_gt_u32_e64 s[54:55], s78, v10
	v_add_u32_e32 v10, 0x8a, v0
	v_cmp_gt_u32_e64 s[24:25], s96, v10
	v_cmp_gt_u32_e64 s[56:57], s78, v10
	v_add_u32_e32 v10, 0x8b, v0
	v_cmp_gt_u32_e64 s[26:27], s96, v10
	v_cmp_gt_u32_e64 s[58:59], s78, v10
	v_add_u32_e32 v10, 0x90, v0
	v_cmp_gt_u32_e64 s[28:29], s96, v10
	v_cmp_gt_u32_e64 s[60:61], s78, v10
	v_add_u32_e32 v10, 0x91, v0
	v_cmp_gt_u32_e64 s[30:31], s96, v10
	v_cmp_gt_u32_e64 s[62:63], s78, v10
	v_add_u32_e32 v10, 0x92, v0
	v_cmp_gt_u32_e64 s[34:35], s96, v10
	v_cmp_gt_u32_e64 s[64:65], s78, v10
	v_add_u32_e32 v10, 0x93, v0
	v_cmp_gt_u32_e64 s[36:37], s96, v10
	v_cmp_gt_u32_e64 s[66:67], s78, v10
	v_add_u32_e32 v10, 0x98, v0
	v_cmp_gt_u32_e64 s[38:39], s96, v10
	v_cmp_gt_u32_e64 s[68:69], s78, v10
	v_add_u32_e32 v10, 0x99, v0
	v_cmp_gt_u32_e64 s[40:41], s96, v10
	v_cmp_gt_u32_e64 s[70:71], s78, v10
	v_add_u32_e32 v10, 0x9a, v0
	v_cmp_gt_u32_e64 s[72:73], s78, v10
	s_or_b64 s[70:71], s[72:73], s[70:71]
	s_or_b64 s[68:69], s[70:71], s[68:69]
	s_or_b64 s[66:67], s[68:69], s[66:67]
	s_or_b64 s[64:65], s[66:67], s[64:65]
	s_or_b64 s[62:63], s[64:65], s[62:63]
	s_or_b64 s[60:61], s[62:63], s[60:61]
	s_or_b64 s[58:59], s[60:61], s[58:59]
	s_or_b64 s[56:57], s[58:59], s[56:57]
	s_or_b64 s[54:55], s[56:57], s[54:55]
	s_or_b64 s[52:53], s[54:55], s[52:53]
	s_or_b64 s[50:51], s[52:53], s[50:51]
	s_or_b64 s[48:49], s[50:51], s[48:49]
	s_or_b64 s[46:47], s[48:49], s[46:47]
	s_or_b64 s[44:45], s[46:47], s[44:45]
	v_add_u32_e32 v0, 0x9b, v0
	v_cmp_gt_u32_e64 s[42:43], s96, v10
	v_cndmask_b32_e64 v62, v184, v62, s[72:73]
	v_cndmask_b32_e64 v61, v184, v61, s[70:71]
	v_cndmask_b32_e64 v60, v184, v60, s[68:69]
	v_cndmask_b32_e64 v59, v184, v59, s[66:67]
	v_cndmask_b32_e64 v58, v184, v58, s[64:65]
	v_cndmask_b32_e64 v57, v184, v57, s[62:63]
	v_cndmask_b32_e64 v56, v184, v56, s[60:61]
	v_cndmask_b32_e64 v55, v184, v55, s[58:59]
	v_cndmask_b32_e64 v54, v184, v54, s[56:57]
	v_cndmask_b32_e64 v53, v184, v53, s[54:55]
	v_cndmask_b32_e64 v52, v184, v52, s[52:53]
	v_cndmask_b32_e64 v51, v184, v51, s[50:51]
	v_cndmask_b32_e64 v50, v184, v50, s[48:49]
	v_cndmask_b32_e64 v49, v184, v49, s[46:47]
	v_cndmask_b32_e64 v48, v184, v48, s[44:45]
	v_cmp_gt_u32_e64 s[44:45], s96, v0
	v_cmp_le_u32_e64 s[46:47], s78, v0
	s_and_saveexec_b64 s[48:49], s[46:47]
	s_mov_b32 s46, 0xf149f2ca
	v_mov_b32_e32 v63, s46
	s_or_b64 exec, exec, s[48:49]
	s_or_b64 s[42:43], s[44:45], s[42:43]
	s_or_b64 s[40:41], s[42:43], s[40:41]
	s_or_b64 s[38:39], s[40:41], s[38:39]
	s_or_b64 s[36:37], s[38:39], s[36:37]
	s_or_b64 s[34:35], s[36:37], s[34:35]
	s_or_b64 s[30:31], s[34:35], s[30:31]
	s_or_b64 s[28:29], s[30:31], s[28:29]
	s_or_b64 s[26:27], s[28:29], s[26:27]
	s_or_b64 s[24:25], s[26:27], s[24:25]
	s_or_b64 s[22:23], s[24:25], s[22:23]
	s_or_b64 s[20:21], s[22:23], s[20:21]
	s_or_b64 s[18:19], s[20:21], s[18:19]
	s_or_b64 s[16:17], s[18:19], s[16:17]
	s_or_b64 s[14:15], s[16:17], s[14:15]
	s_or_b64 vcc, s[14:15], vcc
	v_cndmask_b32_e64 v78, v184, v78, s[42:43]
	v_cndmask_b32_e64 v77, v184, v77, s[40:41]
	v_cndmask_b32_e64 v76, v184, v76, s[38:39]
	v_cndmask_b32_e64 v75, v184, v75, s[36:37]
	v_cndmask_b32_e64 v74, v184, v74, s[34:35]
	v_cndmask_b32_e64 v73, v184, v73, s[30:31]
	v_cndmask_b32_e64 v72, v184, v72, s[28:29]
	v_cndmask_b32_e64 v71, v184, v71, s[26:27]
	v_cndmask_b32_e64 v70, v184, v70, s[24:25]
	v_cndmask_b32_e64 v69, v184, v69, s[22:23]
	v_cndmask_b32_e64 v68, v184, v68, s[20:21]
	v_cndmask_b32_e64 v67, v184, v67, s[18:19]
	v_cndmask_b32_e64 v66, v184, v66, s[16:17]
	v_cndmask_b32_e64 v65, v184, v65, s[14:15]
	v_cndmask_b32_e32 v64, v184, v64, vcc
	v_cndmask_b32_e64 v79, v184, v79, s[44:45]
	s_movk_i32 s65, 0x600
	s_mov_b64 s[66:67], 0x80
	s_mov_b64 s[68:69], 0x1e90c900
